# EpiFFN: adjacent output pairs evaluated together with packed f32 math (v_pk_fma/v_pk_mul/v_pk_add) for centre tap+bias, SiLU scaling and gate product
# baseline (speedup 1.0000x reference)
.LBB0_1404:
	s_add_u32 s16, s10, 0xfffc0080
	s_addc_u32 s17, s11, -1
	s_add_i32 s41, 0, 0x10000
	v_add_u32_e32 v132, s41, v198
	ds_read_b128 v[116:119], v132
	ds_read_b128 v[124:127], v132 offset:1024
	ds_read_b128 v[128:131], v132 offset:2048
	ds_read_b128 v[132:135], v132 offset:3072
	s_cmp_eq_u32 s40, 12
	s_cselect_b32 s35, s6, s17
	s_cselect_b32 s34, s31, s16
	s_cselect_b32 s17, s5, s39
	s_cselect_b32 s16, s36, s37
	v_lshl_add_u64 v[186:187], s[10:11], 0, v[176:177]
	s_add_i32 m0, s33, 0xc000
	ds_read_b128 v[136:139], v199
	ds_read_b128 v[140:143], v199 offset:1024
	ds_read_b128 v[144:147], v199 offset:2048
	ds_read_b128 v[148:151], v199 offset:3072
	ds_read_b128 v[152:155], v199 offset:4096
	ds_read_b128 v[178:181], v199 offset:5120
	ds_read_b128 v[182:185], v199 offset:6144
	ds_read_b128 v[200:203], v199 offset:7168
	global_load_lds_dwordx4 v[186:187], off
	v_lshl_add_u64 v[186:187], s[10:11], 0, v[174:175]
	s_add_i32 m0, s33, 0xe000
	s_nop 0
	global_load_lds_dwordx4 v[186:187], off
	s_waitcnt lgkmcnt(8)
	s_barrier
	s_waitcnt lgkmcnt(0)
	s_setprio 1
	s_waitcnt lgkmcnt(0)
	v_mfma_f32_16x16x32_bf16 v[160:163], v[116:119], v[136:139], v[160:163]
	v_mfma_f32_16x16x32_bf16 v[60:63], v[128:131], v[136:139], v[60:63]
	v_mfma_f32_16x16x32_bf16 v[120:123], v[116:119], v[144:147], v[120:123]
	v_mfma_f32_16x16x32_bf16 v[52:55], v[128:131], v[144:147], v[52:55]
	v_mfma_f32_16x16x32_bf16 v[108:111], v[116:119], v[152:155], v[108:111]
	v_mfma_f32_16x16x32_bf16 v[44:47], v[128:131], v[152:155], v[44:47]
	v_mfma_f32_16x16x32_bf16 v[100:103], v[116:119], v[182:185], v[100:103]
	v_mfma_f32_16x16x32_bf16 v[36:39], v[128:131], v[182:185], v[36:39]
	v_mfma_f32_16x16x32_bf16 v[160:163], v[124:127], v[140:143], v[160:163]
	v_mfma_f32_16x16x32_bf16 v[60:63], v[132:135], v[140:143], v[60:63]
	v_mfma_f32_16x16x32_bf16 v[120:123], v[124:127], v[148:151], v[120:123]
	v_mfma_f32_16x16x32_bf16 v[52:55], v[132:135], v[148:151], v[52:55]
	v_mfma_f32_16x16x32_bf16 v[108:111], v[124:127], v[178:181], v[108:111]
	v_mfma_f32_16x16x32_bf16 v[44:47], v[132:135], v[178:181], v[44:47]
	v_mfma_f32_16x16x32_bf16 v[100:103], v[124:127], v[200:203], v[100:103]
	v_mfma_f32_16x16x32_bf16 v[36:39], v[132:135], v[200:203], v[36:39]
	s_setprio 0
	s_barrier
	s_add_i32 s48, 0, 0x14000
	s_add_i32 s41, s41, s27
	v_add_u32_e32 v164, s48, v198
	v_lshl_add_u64 v[186:187], s[16:17], 0, v[172:173]
	s_mov_b32 m0, s41
	ds_read_b128 v[204:207], v164
	ds_read_b128 v[208:211], v164 offset:1024
	ds_read_b128 v[212:215], v164 offset:2048
	ds_read_b128 v[216:219], v164 offset:3072
	global_load_lds_dwordx4 v[186:187], off
	v_lshl_add_u64 v[186:187], s[16:17], 0, v[168:169]
	s_add_i32 m0, s41, 0x2000
	s_nop 0
	global_load_lds_dwordx4 v[186:187], off
	s_barrier
	s_waitcnt lgkmcnt(0)
	s_setprio 1
	s_waitcnt lgkmcnt(0)
	v_mfma_f32_16x16x32_bf16 v[156:159], v[204:207], v[136:139], v[156:159]
	v_mfma_f32_16x16x32_bf16 v[56:59], v[212:215], v[136:139], v[56:59]
	v_mfma_f32_16x16x32_bf16 v[112:115], v[204:207], v[144:147], v[112:115]
	v_mfma_f32_16x16x32_bf16 v[48:51], v[212:215], v[144:147], v[48:51]
	v_mfma_f32_16x16x32_bf16 v[104:107], v[204:207], v[152:155], v[104:107]
	v_mfma_f32_16x16x32_bf16 v[40:43], v[212:215], v[152:155], v[40:43]
	v_mfma_f32_16x16x32_bf16 v[96:99], v[204:207], v[182:185], v[96:99]
	v_mfma_f32_16x16x32_bf16 v[32:35], v[212:215], v[182:185], v[32:35]
	v_mfma_f32_16x16x32_bf16 v[156:159], v[208:211], v[140:143], v[156:159]
	v_mfma_f32_16x16x32_bf16 v[56:59], v[216:219], v[140:143], v[56:59]
	v_mfma_f32_16x16x32_bf16 v[112:115], v[208:211], v[148:151], v[112:115]
	v_mfma_f32_16x16x32_bf16 v[48:51], v[216:219], v[148:151], v[48:51]
	v_mfma_f32_16x16x32_bf16 v[104:107], v[208:211], v[178:181], v[104:107]
	v_mfma_f32_16x16x32_bf16 v[40:43], v[216:219], v[178:181], v[40:43]
	v_mfma_f32_16x16x32_bf16 v[96:99], v[208:211], v[200:203], v[96:99]
	v_mfma_f32_16x16x32_bf16 v[32:35], v[216:219], v[200:203], v[32:35]
	s_setprio 0
	s_mov_b32 m0, s33
	v_lshl_add_u64 v[186:187], s[34:35], 0, v[170:171]
	s_barrier
	ds_read_b128 v[136:139], v199 offset:16384
	ds_read_b128 v[140:143], v199 offset:17408
	ds_read_b128 v[144:147], v199 offset:18432
	ds_read_b128 v[148:151], v199 offset:19456
	ds_read_b128 v[152:155], v199 offset:20480
	ds_read_b128 v[178:181], v199 offset:21504
	ds_read_b128 v[182:185], v199 offset:22528
	ds_read_b128 v[200:203], v199 offset:23552
	global_load_lds_dwordx4 v[186:187], off
	v_lshl_add_u64 v[220:221], s[34:35], 0, v[166:167]
	s_mov_b32 m0, s2
	s_nop 0
	global_load_lds_dwordx4 v[220:221], off
	s_barrier
	s_waitcnt lgkmcnt(0)
	s_setprio 1
	s_waitcnt lgkmcnt(0)
	v_mfma_f32_16x16x32_bf16 v[92:95], v[116:119], v[136:139], v[92:95]
	v_mfma_f32_16x16x32_bf16 v[28:31], v[128:131], v[136:139], v[28:31]
	v_mfma_f32_16x16x32_bf16 v[84:87], v[116:119], v[144:147], v[84:87]
	v_mfma_f32_16x16x32_bf16 v[20:23], v[128:131], v[144:147], v[20:23]
	v_mfma_f32_16x16x32_bf16 v[76:79], v[116:119], v[152:155], v[76:79]
	v_mfma_f32_16x16x32_bf16 v[12:15], v[128:131], v[152:155], v[12:15]
	v_mfma_f32_16x16x32_bf16 v[68:71], v[116:119], v[182:185], v[68:71]
	v_mfma_f32_16x16x32_bf16 v[4:7], v[128:131], v[182:185], v[4:7]
	v_mfma_f32_16x16x32_bf16 v[92:95], v[124:127], v[140:143], v[92:95]
	v_mfma_f32_16x16x32_bf16 v[28:31], v[132:135], v[140:143], v[28:31]
	v_mfma_f32_16x16x32_bf16 v[84:87], v[124:127], v[148:151], v[84:87]
	v_mfma_f32_16x16x32_bf16 v[20:23], v[132:135], v[148:151], v[20:23]
	v_mfma_f32_16x16x32_bf16 v[76:79], v[124:127], v[178:181], v[76:79]
	v_mfma_f32_16x16x32_bf16 v[12:15], v[132:135], v[178:181], v[12:15]
	v_mfma_f32_16x16x32_bf16 v[68:71], v[124:127], v[200:203], v[68:71]
	v_mfma_f32_16x16x32_bf16 v[4:7], v[132:135], v[200:203], v[4:7]
	s_setprio 0
	s_barrier
	s_add_u32 s52, s16, 0x4000
	s_addc_u32 s53, s17, 0
	s_add_i32 s41, s48, s27
	v_lshl_add_u64 v[116:117], s[52:53], 0, v[172:173]
	s_mov_b32 m0, s41
	s_nop 0
	global_load_lds_dwordx4 v[116:117], off
	v_lshl_add_u64 v[116:117], s[52:53], 0, v[168:169]
	s_add_i32 m0, s41, 0x2000
	s_nop 0
	global_load_lds_dwordx4 v[116:117], off
	s_waitcnt vmcnt(6)
	s_barrier
	s_setprio 1
	v_mfma_f32_16x16x32_bf16 v[88:91], v[204:207], v[136:139], v[88:91]
	v_mfma_f32_16x16x32_bf16 v[24:27], v[212:215], v[136:139], v[24:27]
	v_mfma_f32_16x16x32_bf16 v[80:83], v[204:207], v[144:147], v[80:83]
	v_mfma_f32_16x16x32_bf16 v[16:19], v[212:215], v[144:147], v[16:19]
	v_mfma_f32_16x16x32_bf16 v[72:75], v[204:207], v[152:155], v[72:75]
	v_mfma_f32_16x16x32_bf16 v[8:11], v[212:215], v[152:155], v[8:11]
	v_mfma_f32_16x16x32_bf16 v[64:67], v[204:207], v[182:185], v[64:67]
	v_mfma_f32_16x16x32_bf16 v[0:3], v[212:215], v[182:185], v[0:3]
	v_mfma_f32_16x16x32_bf16 v[88:91], v[208:211], v[140:143], v[88:91]
	v_mfma_f32_16x16x32_bf16 v[24:27], v[216:219], v[140:143], v[24:27]
	v_mfma_f32_16x16x32_bf16 v[80:83], v[208:211], v[148:151], v[80:83]
	v_mfma_f32_16x16x32_bf16 v[16:19], v[216:219], v[148:151], v[16:19]
	v_mfma_f32_16x16x32_bf16 v[72:75], v[208:211], v[178:181], v[72:75]
	v_mfma_f32_16x16x32_bf16 v[8:11], v[216:219], v[178:181], v[8:11]
	v_mfma_f32_16x16x32_bf16 v[64:67], v[208:211], v[200:203], v[64:67]
	v_mfma_f32_16x16x32_bf16 v[0:3], v[216:219], v[200:203], v[0:3]
	s_setprio 0
	s_add_i32 s41, 0, 0x18000
	v_add_u32_e32 v132, s41, v198
	s_barrier
	ds_read_b128 v[116:119], v132
	ds_read_b128 v[124:127], v132 offset:1024
	ds_read_b128 v[128:131], v132 offset:2048
	ds_read_b128 v[132:135], v132 offset:3072
	s_add_u32 s34, s34, 0x40000
	s_addc_u32 s35, s35, 0
	s_mov_b32 m0, s78
	v_lshl_add_u64 v[204:205], s[34:35], 0, v[170:171]
	ds_read_b128 v[136:139], v199 offset:32768
	ds_read_b128 v[140:143], v199 offset:33792
	ds_read_b128 v[144:147], v199 offset:34816
	ds_read_b128 v[148:151], v199 offset:35840
	ds_read_b128 v[152:155], v199 offset:36864
	ds_read_b128 v[178:181], v199 offset:37888
	ds_read_b128 v[182:185], v199 offset:38912
	ds_read_b128 v[200:203], v199 offset:39936
	global_load_lds_dwordx4 v[204:205], off
	v_lshl_add_u64 v[204:205], s[34:35], 0, v[166:167]
	s_mov_b32 m0, s79
	s_nop 0
	global_load_lds_dwordx4 v[204:205], off
	s_waitcnt lgkmcnt(8)
	s_barrier
	s_waitcnt lgkmcnt(0)
	s_setprio 1
	s_waitcnt lgkmcnt(0)
	v_mfma_f32_16x16x32_bf16 v[160:163], v[116:119], v[136:139], v[160:163]
	v_mfma_f32_16x16x32_bf16 v[60:63], v[128:131], v[136:139], v[60:63]
	v_mfma_f32_16x16x32_bf16 v[120:123], v[116:119], v[144:147], v[120:123]
	v_mfma_f32_16x16x32_bf16 v[52:55], v[128:131], v[144:147], v[52:55]
	v_mfma_f32_16x16x32_bf16 v[108:111], v[116:119], v[152:155], v[108:111]
	v_mfma_f32_16x16x32_bf16 v[44:47], v[128:131], v[152:155], v[44:47]
	v_mfma_f32_16x16x32_bf16 v[100:103], v[116:119], v[182:185], v[100:103]
	v_mfma_f32_16x16x32_bf16 v[36:39], v[128:131], v[182:185], v[36:39]
	v_mfma_f32_16x16x32_bf16 v[160:163], v[124:127], v[140:143], v[160:163]
	v_mfma_f32_16x16x32_bf16 v[60:63], v[132:135], v[140:143], v[60:63]
	v_mfma_f32_16x16x32_bf16 v[120:123], v[124:127], v[148:151], v[120:123]
	v_mfma_f32_16x16x32_bf16 v[52:55], v[132:135], v[148:151], v[52:55]
	v_mfma_f32_16x16x32_bf16 v[108:111], v[124:127], v[178:181], v[108:111]
	v_mfma_f32_16x16x32_bf16 v[44:47], v[132:135], v[178:181], v[44:47]
	v_mfma_f32_16x16x32_bf16 v[100:103], v[124:127], v[200:203], v[100:103]
	v_mfma_f32_16x16x32_bf16 v[36:39], v[132:135], v[200:203], v[36:39]
	s_setprio 0
	s_barrier
	s_add_i32 s48, 0, 0x1c000
	s_add_u32 s34, s16, 0x8000
	s_addc_u32 s35, s17, 0
	s_add_i32 s41, s41, s27
	v_add_u32_e32 v164, s48, v198
	v_lshl_add_u64 v[222:223], s[34:35], 0, v[172:173]
	s_mov_b32 m0, s41
	ds_read_b128 v[204:207], v164
	ds_read_b128 v[208:211], v164 offset:1024
	ds_read_b128 v[212:215], v164 offset:2048
	ds_read_b128 v[216:219], v164 offset:3072
	global_load_lds_dwordx4 v[222:223], off
	v_lshl_add_u64 v[222:223], s[34:35], 0, v[168:169]
	s_add_i32 m0, s41, 0x2000
	s_nop 0
	global_load_lds_dwordx4 v[222:223], off
	s_barrier
	s_waitcnt lgkmcnt(0)
	s_setprio 1
	s_waitcnt lgkmcnt(0)
	v_mfma_f32_16x16x32_bf16 v[156:159], v[204:207], v[136:139], v[156:159]
	v_mfma_f32_16x16x32_bf16 v[56:59], v[212:215], v[136:139], v[56:59]
	v_mfma_f32_16x16x32_bf16 v[112:115], v[204:207], v[144:147], v[112:115]
	v_mfma_f32_16x16x32_bf16 v[48:51], v[212:215], v[144:147], v[48:51]
	v_mfma_f32_16x16x32_bf16 v[104:107], v[204:207], v[152:155], v[104:107]
	v_mfma_f32_16x16x32_bf16 v[40:43], v[212:215], v[152:155], v[40:43]
	v_mfma_f32_16x16x32_bf16 v[96:99], v[204:207], v[182:185], v[96:99]
	v_mfma_f32_16x16x32_bf16 v[32:35], v[212:215], v[182:185], v[32:35]
	v_mfma_f32_16x16x32_bf16 v[156:159], v[208:211], v[140:143], v[156:159]
	v_mfma_f32_16x16x32_bf16 v[56:59], v[216:219], v[140:143], v[56:59]
	v_mfma_f32_16x16x32_bf16 v[112:115], v[208:211], v[148:151], v[112:115]
	v_mfma_f32_16x16x32_bf16 v[48:51], v[216:219], v[148:151], v[48:51]
	v_mfma_f32_16x16x32_bf16 v[104:107], v[208:211], v[178:181], v[104:107]
	v_mfma_f32_16x16x32_bf16 v[40:43], v[216:219], v[178:181], v[40:43]
	v_mfma_f32_16x16x32_bf16 v[96:99], v[208:211], v[200:203], v[96:99]
	v_mfma_f32_16x16x32_bf16 v[32:35], v[216:219], v[200:203], v[32:35]
	s_setprio 0
	s_mov_b32 m0, s82
	v_lshl_add_u64 v[186:187], v[186:187], 0, s[18:19]
	s_barrier
	ds_read_b128 v[136:139], v199 offset:49152
	ds_read_b128 v[140:143], v199 offset:50176
	ds_read_b128 v[144:147], v199 offset:51200
	ds_read_b128 v[148:151], v199 offset:52224
	ds_read_b128 v[152:155], v199 offset:53248
	ds_read_b128 v[178:181], v199 offset:54272
	ds_read_b128 v[182:185], v199 offset:55296
	ds_read_b128 v[200:203], v199 offset:56320
	global_load_lds_dwordx4 v[186:187], off
	v_lshl_add_u64 v[186:187], v[220:221], 0, s[18:19]
	s_mov_b32 m0, s83
	s_nop 0
	global_load_lds_dwordx4 v[186:187], off
	s_barrier
	s_waitcnt lgkmcnt(0)
	s_setprio 1
	s_waitcnt lgkmcnt(0)
	v_mfma_f32_16x16x32_bf16 v[92:95], v[116:119], v[136:139], v[92:95]
	v_mfma_f32_16x16x32_bf16 v[28:31], v[128:131], v[136:139], v[28:31]
	v_mfma_f32_16x16x32_bf16 v[84:87], v[116:119], v[144:147], v[84:87]
	v_mfma_f32_16x16x32_bf16 v[20:23], v[128:131], v[144:147], v[20:23]
	v_mfma_f32_16x16x32_bf16 v[76:79], v[116:119], v[152:155], v[76:79]
	v_mfma_f32_16x16x32_bf16 v[12:15], v[128:131], v[152:155], v[12:15]
	v_mfma_f32_16x16x32_bf16 v[68:71], v[116:119], v[182:185], v[68:71]
	v_mfma_f32_16x16x32_bf16 v[4:7], v[128:131], v[182:185], v[4:7]
	v_mfma_f32_16x16x32_bf16 v[92:95], v[124:127], v[140:143], v[92:95]
	v_mfma_f32_16x16x32_bf16 v[28:31], v[132:135], v[140:143], v[28:31]
	v_mfma_f32_16x16x32_bf16 v[84:87], v[124:127], v[148:151], v[84:87]
	v_mfma_f32_16x16x32_bf16 v[20:23], v[132:135], v[148:151], v[20:23]
	v_mfma_f32_16x16x32_bf16 v[76:79], v[124:127], v[178:181], v[76:79]
	v_mfma_f32_16x16x32_bf16 v[12:15], v[132:135], v[178:181], v[12:15]
	v_mfma_f32_16x16x32_bf16 v[68:71], v[124:127], v[200:203], v[68:71]
	v_mfma_f32_16x16x32_bf16 v[4:7], v[132:135], v[200:203], v[4:7]
	s_setprio 0
	s_barrier
	s_add_u32 s16, s16, 0xc000
	s_addc_u32 s17, s17, 0
	s_add_i32 s34, s48, s27
	v_lshl_add_u64 v[116:117], s[16:17], 0, v[172:173]
	s_mov_b32 m0, s34
	s_nop 0
	global_load_lds_dwordx4 v[116:117], off
	v_lshl_add_u64 v[116:117], s[16:17], 0, v[168:169]
	s_add_i32 m0, s34, 0x2000
	s_nop 0
	global_load_lds_dwordx4 v[116:117], off
	s_waitcnt vmcnt(6)
	s_barrier
	s_setprio 1
	v_mfma_f32_16x16x32_bf16 v[88:91], v[204:207], v[136:139], v[88:91]
	v_mfma_f32_16x16x32_bf16 v[24:27], v[212:215], v[136:139], v[24:27]
	v_mfma_f32_16x16x32_bf16 v[80:83], v[204:207], v[144:147], v[80:83]
	v_mfma_f32_16x16x32_bf16 v[16:19], v[212:215], v[144:147], v[16:19]
	v_mfma_f32_16x16x32_bf16 v[72:75], v[204:207], v[152:155], v[72:75]
	v_mfma_f32_16x16x32_bf16 v[8:11], v[212:215], v[152:155], v[8:11]
	v_mfma_f32_16x16x32_bf16 v[64:67], v[204:207], v[182:185], v[64:67]
	v_mfma_f32_16x16x32_bf16 v[0:3], v[212:215], v[182:185], v[0:3]
	v_mfma_f32_16x16x32_bf16 v[88:91], v[208:211], v[140:143], v[88:91]
	v_mfma_f32_16x16x32_bf16 v[24:27], v[216:219], v[140:143], v[24:27]
	v_mfma_f32_16x16x32_bf16 v[80:83], v[208:211], v[148:151], v[80:83]
	v_mfma_f32_16x16x32_bf16 v[16:19], v[216:219], v[148:151], v[16:19]
	v_mfma_f32_16x16x32_bf16 v[72:75], v[208:211], v[178:181], v[72:75]
	v_mfma_f32_16x16x32_bf16 v[8:11], v[216:219], v[178:181], v[8:11]
	v_mfma_f32_16x16x32_bf16 v[64:67], v[208:211], v[200:203], v[64:67]
	v_mfma_f32_16x16x32_bf16 v[0:3], v[216:219], v[200:203], v[0:3]
	s_setprio 0
	s_add_i32 s40, s40, 2
	s_add_u32 s37, s37, 0x10000
	s_addc_u32 s39, s39, 0
	s_add_u32 s10, s10, 0x100
	s_addc_u32 s11, s11, 0
	s_cmp_gt_u32 s40, 13
	s_barrier
	s_cbranch_scc0 .LBB0_1404
	v_mov_b32_e32 v116, v188
	s_lshl_b32 s6, s38, 7
	v_readfirstlane_b32 s10, v116
	s_lshr_b32 s5, s10, 1
	v_and_b32_e32 v200, 15, v116
	s_and_b32 s5, s5, 0x60
	v_lshrrev_b32_e32 v116, 1, v116
	s_or_b32 s6, s5, s6
	v_and_b32_e32 v116, 24, v116
	v_or_b32_e32 v182, s6, v116
	v_ashrrev_i32_e32 v183, 31, v182
	v_lshlrev_b64 v[118:119], 2, v[182:183]
	v_lshl_add_u64 v[184:185], s[42:43], 0, v[118:119]
	global_load_dwordx4 v[124:127], v[184:185], off
	v_lshl_add_u64 v[128:129], s[58:59], 0, v[118:119]
	global_load_dwordx4 v[128:131], v[128:129], off
	v_lshl_add_u64 v[132:133], s[60:61], 0, v[118:119]
	global_load_dwordx4 v[132:135], v[132:133], off
	v_lshl_add_u64 v[186:187], s[46:47], 0, v[118:119]
	global_load_dwordx4 v[136:139], v[186:187], off
	v_lshl_add_u64 v[140:141], s[12:13], 0, v[118:119]
	global_load_dwordx4 v[140:143], v[140:141], off
	v_lshl_add_u64 v[144:145], s[50:51], 0, v[118:119]
	global_load_dwordx4 v[144:147], v[144:145], off
	v_lshl_add_u64 v[148:149], s[20:21], 0, v[118:119]
	global_load_dwordx4 v[148:151], v[148:149], off
	v_lshl_add_u64 v[118:119], s[44:45], 0, v[118:119]
	global_load_dwordx4 v[152:155], v[118:119], off
	v_mov_b32_e32 v254, 0xbfb8aa3b
	v_mov_b32_e32 v255, 0xbfb8aa3b
	v_mov_b32_e32 v252, 1.0
	v_mov_b32_e32 v253, 1.0
	v_cmp_eq_u32_e32 vcc, 15, v200
	v_cmp_eq_u32_e64 s[34:35], 0, v200
	s_nop 0
	s_nop 0
	v_mov_b32_e32 v180, v165
	s_lshl_b32 s11, s7, 8
	s_ashr_i32 s7, s10, 2
	s_andn2_b32 s7, s7, 63
	s_add_i32 s31, s7, s11
	v_mov_b32_e32 v181, v165
	s_ashr_i32 s10, s31, 6
	s_ashr_i32 s11, s10, 31
	s_lshl_b32 s16, s38, 8
	s_lshl_b64 s[52:53], s[10:11], 2
	v_cmp_gt_u32_e64 s[36:37], 2, v200
	s_ashr_i32 s17, s16, 31
	v_or_b32_e32 v183, s52, v200
	s_waitcnt vmcnt(0)
	v_cndmask_b32_e64 v204, v160, 0, vcc
	v_cndmask_b32_e64 v205, v161, 0, vcc
	v_cndmask_b32_e64 v206, v156, 0, vcc
	v_cndmask_b32_e64 v207, v157, 0, vcc
	v_pk_fma_f32 v[208:209], v[160:161], v[128:129], v[136:137]
	v_pk_fma_f32 v[210:211], v[156:157], v[144:145], v[152:153]
	v_fmac_f32_dpp v208, v204, v124 row_ror:1 row_mask:0xf bank_mask:0xf bound_ctrl:1
	v_fmac_f32_dpp v209, v205, v125 row_ror:1 row_mask:0xf bank_mask:0xf bound_ctrl:1
	v_fmac_f32_dpp v210, v206, v140 row_ror:1 row_mask:0xf bank_mask:0xf bound_ctrl:1
	v_fmac_f32_dpp v211, v207, v141 row_ror:1 row_mask:0xf bank_mask:0xf bound_ctrl:1
	v_cndmask_b32_e64 v204, v160, v120, s[34:35]
	v_cndmask_b32_e64 v205, v161, v121, s[34:35]
	v_cndmask_b32_e64 v206, v156, v112, s[34:35]
	v_cndmask_b32_e64 v207, v157, v113, s[34:35]
	v_fmac_f32_dpp v208, v204, v132 row_ror:15 row_mask:0xf bank_mask:0xf
	v_fmac_f32_dpp v209, v205, v133 row_ror:15 row_mask:0xf bank_mask:0xf
	v_fmac_f32_dpp v210, v206, v148 row_ror:15 row_mask:0xf bank_mask:0xf
	v_fmac_f32_dpp v211, v207, v149 row_ror:15 row_mask:0xf bank_mask:0xf
	v_pk_mul_f32 v[212:213], v[254:255], v[208:209]
	v_exp_f32_e32 v212, v212
	v_exp_f32_e32 v213, v213
	s_nop 0
	v_pk_add_f32 v[212:213], v[212:213], v[252:253]
	v_rcp_f32_e32 v212, v212
	v_rcp_f32_e32 v213, v213
	s_nop 0
	v_pk_mul_f32 v[208:209], v[208:209], v[212:213]
	v_pk_mul_f32 v[210:211], v[210:211], v[208:209]
	v_cndmask_b32_e64 v214, v162, 0, vcc
	v_cndmask_b32_e64 v215, v163, 0, vcc
	v_cndmask_b32_e64 v220, v158, 0, vcc
	v_cndmask_b32_e64 v221, v159, 0, vcc
	v_pk_fma_f32 v[222:223], v[162:163], v[130:131], v[138:139]
	v_pk_fma_f32 v[240:241], v[158:159], v[146:147], v[154:155]
	v_fmac_f32_dpp v222, v214, v126 row_ror:1 row_mask:0xf bank_mask:0xf bound_ctrl:1
	v_fmac_f32_dpp v223, v215, v127 row_ror:1 row_mask:0xf bank_mask:0xf bound_ctrl:1
	v_fmac_f32_dpp v240, v220, v142 row_ror:1 row_mask:0xf bank_mask:0xf bound_ctrl:1
	v_fmac_f32_dpp v241, v221, v143 row_ror:1 row_mask:0xf bank_mask:0xf bound_ctrl:1
	v_cndmask_b32_e64 v214, v162, v122, s[34:35]
	v_cndmask_b32_e64 v215, v163, v123, s[34:35]
	v_cndmask_b32_e64 v220, v158, v114, s[34:35]
	v_cndmask_b32_e64 v221, v159, v115, s[34:35]
	v_fmac_f32_dpp v222, v214, v134 row_ror:15 row_mask:0xf bank_mask:0xf
	v_fmac_f32_dpp v223, v215, v135 row_ror:15 row_mask:0xf bank_mask:0xf
	v_fmac_f32_dpp v240, v220, v150 row_ror:15 row_mask:0xf bank_mask:0xf
	v_fmac_f32_dpp v241, v221, v151 row_ror:15 row_mask:0xf bank_mask:0xf
	v_pk_mul_f32 v[242:243], v[254:255], v[222:223]
	v_exp_f32_e32 v242, v242
	v_exp_f32_e32 v243, v243
	s_nop 0
	v_pk_add_f32 v[242:243], v[242:243], v[252:253]
	v_rcp_f32_e32 v242, v242
	v_rcp_f32_e32 v243, v243
	s_nop 0
	v_pk_mul_f32 v[222:223], v[222:223], v[242:243]
	v_pk_mul_f32 v[240:241], v[240:241], v[222:223]
	s_nop 1
	s_nop 0
	v_cvt_pk_bf16_f32 v118, v210, v211
	v_lshlrev_b32_e32 v178, 1, v116
	v_cvt_pk_bf16_f32 v119, v240, v241
	s_and_saveexec_b64 s[10:11], s[36:37]
	s_cbranch_execz .LBB0_1407
	v_mov_b64_e32 v[116:117], s[0:1]
	v_mad_i64_i32 v[116:117], s[38:39], v183, s66, v[116:117]
	v_lshl_add_u64 v[116:117], s[16:17], 1, v[116:117]
	s_lshl_b32 s48, s5, 1
	v_lshl_add_u64 v[116:117], v[116:117], 0, s[48:49]
	v_mov_b32_e32 v179, v165
	v_lshl_add_u64 v[116:117], v[116:117], 0, v[178:179]
	v_cvt_pk_bf16_f32 v180, v160, v161
	v_cvt_pk_bf16_f32 v181, v162, v163
	global_store_dwordx2 v[116:117], v[180:181], off
	v_cvt_pk_bf16_f32 v180, v156, v157
	v_cvt_pk_bf16_f32 v181, v158, v159
	global_store_dwordx2 v[116:117], v[180:181], off offset:256
.LBB0_1407:
	s_or_b64 exec, exec, s[10:11]
	v_cndmask_b32_e64 v244, v120, v160, vcc
	v_cndmask_b32_e64 v245, v121, v161, vcc
	v_cndmask_b32_e64 v246, v112, v156, vcc
	v_cndmask_b32_e64 v247, v113, v157, vcc
	v_pk_fma_f32 v[248:249], v[120:121], v[128:129], v[136:137]
	v_pk_fma_f32 v[250:251], v[112:113], v[144:145], v[152:153]
	v_fmac_f32_dpp v248, v244, v124 row_ror:1 row_mask:0xf bank_mask:0xf bound_ctrl:1
	v_fmac_f32_dpp v249, v245, v125 row_ror:1 row_mask:0xf bank_mask:0xf bound_ctrl:1
	v_fmac_f32_dpp v250, v246, v140 row_ror:1 row_mask:0xf bank_mask:0xf bound_ctrl:1
	v_fmac_f32_dpp v251, v247, v141 row_ror:1 row_mask:0xf bank_mask:0xf bound_ctrl:1
	v_cndmask_b32_e64 v244, v120, v108, s[34:35]
	v_cndmask_b32_e64 v245, v121, v109, s[34:35]
	v_cndmask_b32_e64 v246, v112, v104, s[34:35]
	v_cndmask_b32_e64 v247, v113, v105, s[34:35]
	v_fmac_f32_dpp v248, v244, v132 row_ror:15 row_mask:0xf bank_mask:0xf
	v_fmac_f32_dpp v249, v245, v133 row_ror:15 row_mask:0xf bank_mask:0xf
	v_fmac_f32_dpp v250, v246, v148 row_ror:15 row_mask:0xf bank_mask:0xf
	v_fmac_f32_dpp v251, v247, v149 row_ror:15 row_mask:0xf bank_mask:0xf
	v_pk_mul_f32 v[204:205], v[254:255], v[248:249]
	v_exp_f32_e32 v204, v204
	v_exp_f32_e32 v205, v205
	s_nop 0
	v_pk_add_f32 v[204:205], v[204:205], v[252:253]
	v_rcp_f32_e32 v204, v204
	v_rcp_f32_e32 v205, v205
	s_nop 0
	v_pk_mul_f32 v[248:249], v[248:249], v[204:205]
	v_pk_mul_f32 v[250:251], v[250:251], v[248:249]
	s_nop 0
	s_nop 0
	s_nop 0
	s_nop 0
	v_cndmask_b32_e64 v206, v108, v120, vcc
	v_cndmask_b32_e64 v207, v109, v121, vcc
	v_cndmask_b32_e64 v208, v104, v112, vcc
	v_cndmask_b32_e64 v209, v105, v113, vcc
	v_pk_fma_f32 v[212:213], v[108:109], v[128:129], v[136:137]
	v_pk_fma_f32 v[214:215], v[104:105], v[144:145], v[152:153]
	v_fmac_f32_dpp v212, v206, v124 row_ror:1 row_mask:0xf bank_mask:0xf bound_ctrl:1
	v_fmac_f32_dpp v213, v207, v125 row_ror:1 row_mask:0xf bank_mask:0xf bound_ctrl:1
	v_fmac_f32_dpp v214, v208, v140 row_ror:1 row_mask:0xf bank_mask:0xf bound_ctrl:1
	v_fmac_f32_dpp v215, v209, v141 row_ror:1 row_mask:0xf bank_mask:0xf bound_ctrl:1
	v_cndmask_b32_e64 v206, v108, v100, s[34:35]
	v_cndmask_b32_e64 v207, v109, v101, s[34:35]
	v_cndmask_b32_e64 v208, v104, v96, s[34:35]
	v_cndmask_b32_e64 v209, v105, v97, s[34:35]
	v_fmac_f32_dpp v212, v206, v132 row_ror:15 row_mask:0xf bank_mask:0xf
	v_fmac_f32_dpp v213, v207, v133 row_ror:15 row_mask:0xf bank_mask:0xf
	v_fmac_f32_dpp v214, v208, v148 row_ror:15 row_mask:0xf bank_mask:0xf
	v_fmac_f32_dpp v215, v209, v149 row_ror:15 row_mask:0xf bank_mask:0xf
	v_pk_mul_f32 v[220:221], v[254:255], v[212:213]
	v_exp_f32_e32 v220, v220
	v_exp_f32_e32 v221, v221
	s_nop 0
	v_pk_add_f32 v[220:221], v[220:221], v[252:253]
	v_rcp_f32_e32 v220, v220
	v_rcp_f32_e32 v221, v221
	s_nop 0
	v_pk_mul_f32 v[212:213], v[212:213], v[220:221]
	v_pk_mul_f32 v[214:215], v[214:215], v[212:213]
	s_nop 0
	v_cndmask_b32_e64 v222, v122, v162, vcc
	v_cndmask_b32_e64 v223, v123, v163, vcc
	v_cndmask_b32_e64 v242, v114, v158, vcc
	v_cndmask_b32_e64 v243, v115, v159, vcc
	v_pk_fma_f32 v[210:211], v[122:123], v[130:131], v[138:139]
	v_pk_fma_f32 v[240:241], v[114:115], v[146:147], v[154:155]
	v_fmac_f32_dpp v210, v222, v126 row_ror:1 row_mask:0xf bank_mask:0xf bound_ctrl:1
	v_fmac_f32_dpp v211, v223, v127 row_ror:1 row_mask:0xf bank_mask:0xf bound_ctrl:1
	v_fmac_f32_dpp v240, v242, v142 row_ror:1 row_mask:0xf bank_mask:0xf bound_ctrl:1
	v_fmac_f32_dpp v241, v243, v143 row_ror:1 row_mask:0xf bank_mask:0xf bound_ctrl:1
	v_cndmask_b32_e64 v222, v122, v110, s[34:35]
	v_cndmask_b32_e64 v223, v123, v111, s[34:35]
	v_cndmask_b32_e64 v242, v114, v106, s[34:35]
	v_cndmask_b32_e64 v243, v115, v107, s[34:35]
	v_fmac_f32_dpp v210, v222, v134 row_ror:15 row_mask:0xf bank_mask:0xf
	v_fmac_f32_dpp v211, v223, v135 row_ror:15 row_mask:0xf bank_mask:0xf
	v_fmac_f32_dpp v240, v242, v150 row_ror:15 row_mask:0xf bank_mask:0xf
	v_fmac_f32_dpp v241, v243, v151 row_ror:15 row_mask:0xf bank_mask:0xf
	v_pk_mul_f32 v[244:245], v[254:255], v[210:211]
	v_exp_f32_e32 v244, v244
	v_exp_f32_e32 v245, v245
	s_nop 0
	v_pk_add_f32 v[244:245], v[244:245], v[252:253]
	v_rcp_f32_e32 v244, v244
	v_rcp_f32_e32 v245, v245
	s_nop 0
	v_pk_mul_f32 v[210:211], v[210:211], v[244:245]
	v_pk_mul_f32 v[240:241], v[240:241], v[210:211]
	s_nop 0
	s_nop 0
	s_nop 0
	s_nop 0
	v_cvt_pk_bf16_f32 v116, v250, v251
	v_cvt_pk_bf16_f32 v117, v240, v241
	s_nop 0
	s_nop 0
	v_cndmask_b32_e64 v246, v110, v122, vcc
	v_cndmask_b32_e64 v247, v111, v123, vcc
	v_cndmask_b32_e64 v248, v106, v114, vcc
	v_cndmask_b32_e64 v249, v107, v115, vcc
	v_pk_fma_f32 v[204:205], v[110:111], v[130:131], v[138:139]
	v_pk_fma_f32 v[206:207], v[106:107], v[146:147], v[154:155]
	v_fmac_f32_dpp v204, v246, v126 row_ror:1 row_mask:0xf bank_mask:0xf bound_ctrl:1
	v_fmac_f32_dpp v205, v247, v127 row_ror:1 row_mask:0xf bank_mask:0xf bound_ctrl:1
	v_fmac_f32_dpp v206, v248, v142 row_ror:1 row_mask:0xf bank_mask:0xf bound_ctrl:1
	v_fmac_f32_dpp v207, v249, v143 row_ror:1 row_mask:0xf bank_mask:0xf bound_ctrl:1
	v_cndmask_b32_e64 v246, v110, v102, s[34:35]
	v_cndmask_b32_e64 v247, v111, v103, s[34:35]
	v_cndmask_b32_e64 v248, v106, v98, s[34:35]
	v_cndmask_b32_e64 v249, v107, v99, s[34:35]
	v_fmac_f32_dpp v204, v246, v134 row_ror:15 row_mask:0xf bank_mask:0xf
	v_fmac_f32_dpp v205, v247, v135 row_ror:15 row_mask:0xf bank_mask:0xf
	v_fmac_f32_dpp v206, v248, v150 row_ror:15 row_mask:0xf bank_mask:0xf
	v_fmac_f32_dpp v207, v249, v151 row_ror:15 row_mask:0xf bank_mask:0xf
	v_pk_mul_f32 v[208:209], v[254:255], v[204:205]
	v_exp_f32_e32 v208, v208
	v_exp_f32_e32 v209, v209
	s_nop 0
	v_pk_add_f32 v[208:209], v[208:209], v[252:253]
	v_rcp_f32_e32 v208, v208
	v_rcp_f32_e32 v209, v209
	s_nop 0
	v_pk_mul_f32 v[204:205], v[204:205], v[208:209]
	v_pk_mul_f32 v[206:207], v[206:207], v[204:205]
	s_nop 0
	s_nop 0
	s_nop 0
	s_nop 0
	v_cndmask_b32_e64 v212, v100, v108, vcc
	v_cndmask_b32_e64 v213, v101, v109, vcc
	v_cndmask_b32_e64 v220, v96, v104, vcc
	v_cndmask_b32_e64 v221, v97, v105, vcc
	v_pk_fma_f32 v[222:223], v[100:101], v[128:129], v[136:137]
	v_pk_fma_f32 v[242:243], v[96:97], v[144:145], v[152:153]
	v_fmac_f32_dpp v222, v212, v124 row_ror:1 row_mask:0xf bank_mask:0xf bound_ctrl:1
	v_fmac_f32_dpp v223, v213, v125 row_ror:1 row_mask:0xf bank_mask:0xf bound_ctrl:1
	v_fmac_f32_dpp v242, v220, v140 row_ror:1 row_mask:0xf bank_mask:0xf bound_ctrl:1
	v_fmac_f32_dpp v243, v221, v141 row_ror:1 row_mask:0xf bank_mask:0xf bound_ctrl:1
	v_cndmask_b32_e64 v212, v100, 0, s[34:35]
	v_cndmask_b32_e64 v213, v101, 0, s[34:35]
	v_cndmask_b32_e64 v220, v96, 0, s[34:35]
	v_cndmask_b32_e64 v221, v97, 0, s[34:35]
	v_fmac_f32_dpp v222, v212, v132 row_ror:15 row_mask:0xf bank_mask:0xf
	v_fmac_f32_dpp v223, v213, v133 row_ror:15 row_mask:0xf bank_mask:0xf
	v_fmac_f32_dpp v242, v220, v148 row_ror:15 row_mask:0xf bank_mask:0xf
	v_fmac_f32_dpp v243, v221, v149 row_ror:15 row_mask:0xf bank_mask:0xf
	v_pk_mul_f32 v[210:211], v[254:255], v[222:223]
	v_exp_f32_e32 v210, v210
	v_exp_f32_e32 v211, v211
	s_nop 0
	v_pk_add_f32 v[210:211], v[210:211], v[252:253]
	v_rcp_f32_e32 v210, v210
	v_rcp_f32_e32 v211, v211
	s_nop 0
	v_pk_mul_f32 v[222:223], v[222:223], v[210:211]
	v_pk_mul_f32 v[242:243], v[242:243], v[222:223]
	v_cvt_pk_bf16_f32 v112, v214, v215
	v_cvt_pk_bf16_f32 v113, v206, v207
	s_nop 0
	s_nop 0
	s_nop 0
	s_nop 0
	v_cndmask_b32_e64 v244, v102, v110, vcc
	v_cndmask_b32_e64 v245, v103, v111, vcc
	v_cndmask_b32_e64 v250, v98, v106, vcc
	v_cndmask_b32_e64 v251, v99, v107, vcc
	v_pk_fma_f32 v[240:241], v[102:103], v[130:131], v[138:139]
	v_pk_fma_f32 v[246:247], v[98:99], v[146:147], v[154:155]
	v_fmac_f32_dpp v240, v244, v126 row_ror:1 row_mask:0xf bank_mask:0xf bound_ctrl:1
	v_fmac_f32_dpp v241, v245, v127 row_ror:1 row_mask:0xf bank_mask:0xf bound_ctrl:1
	v_fmac_f32_dpp v246, v250, v142 row_ror:1 row_mask:0xf bank_mask:0xf bound_ctrl:1
	v_fmac_f32_dpp v247, v251, v143 row_ror:1 row_mask:0xf bank_mask:0xf bound_ctrl:1
	v_cndmask_b32_e64 v244, v102, 0, s[34:35]
	v_cndmask_b32_e64 v245, v103, 0, s[34:35]
	v_cndmask_b32_e64 v250, v98, 0, s[34:35]
	v_cndmask_b32_e64 v251, v99, 0, s[34:35]
	v_fmac_f32_dpp v240, v244, v134 row_ror:15 row_mask:0xf bank_mask:0xf
	v_fmac_f32_dpp v241, v245, v135 row_ror:15 row_mask:0xf bank_mask:0xf
	v_fmac_f32_dpp v246, v250, v150 row_ror:15 row_mask:0xf bank_mask:0xf
	v_fmac_f32_dpp v247, v251, v151 row_ror:15 row_mask:0xf bank_mask:0xf
	v_pk_mul_f32 v[248:249], v[254:255], v[240:241]
	v_exp_f32_e32 v248, v248
	v_exp_f32_e32 v249, v249
	s_nop 0
	v_pk_add_f32 v[248:249], v[248:249], v[252:253]
	v_rcp_f32_e32 v248, v248
	v_rcp_f32_e32 v249, v249
	s_nop 0
	v_pk_mul_f32 v[240:241], v[240:241], v[248:249]
	v_pk_mul_f32 v[246:247], v[246:247], v[240:241]
	s_nop 0
	s_nop 0
	s_nop 0
	s_nop 0
	v_cmp_lt_u32_e64 s[38:39], 13, v200
	v_add_u32_e32 v180, -12, v200
	v_cvt_pk_bf16_f32 v104, v242, v243
	v_cvt_pk_bf16_f32 v105, v246, v247
	s_and_saveexec_b64 s[10:11], s[38:39]
	s_cbranch_execz .LBB0_1409
	v_mov_b32_e32 v181, v165
	v_lshl_add_u64 v[106:107], s[52:53], 0, v[180:181]
	v_mov_b64_e32 v[108:109], s[0:1]
	s_movk_i32 s48, 0x2c00
	v_mad_u64_u32 v[108:109], s[40:41], v106, s48, v[108:109]
	v_mad_i32_i24 v109, v107, s48, v109
	v_lshl_add_u64 v[106:107], s[16:17], 1, v[108:109]
	s_lshl_b32 s48, s5, 1
	v_lshl_add_u64 v[106:107], v[106:107], 0, s[48:49]
	v_mov_b32_e32 v179, v165
	s_movk_i32 s66, 0x2c00
	v_lshl_add_u64 v[106:107], v[106:107], 0, v[178:179]
	v_cvt_pk_bf16_f32 v100, v100, v101
	v_cvt_pk_bf16_f32 v101, v102, v103
	global_store_dwordx2 v[106:107], v[100:101], off
	v_cvt_pk_bf16_f32 v96, v96, v97
	v_cvt_pk_bf16_f32 v97, v98, v99
	global_store_dwordx2 v[106:107], v[96:97], off offset:256
.LBB0_1409:
	s_or_b64 exec, exec, s[10:11]
	v_cndmask_b32_e64 v204, v92, 0, vcc
	v_cndmask_b32_e64 v205, v93, 0, vcc
	v_cndmask_b32_e64 v208, v88, 0, vcc
	v_cndmask_b32_e64 v209, v89, 0, vcc
	v_pk_fma_f32 v[212:213], v[92:93], v[128:129], v[136:137]
	v_pk_fma_f32 v[220:221], v[88:89], v[144:145], v[152:153]
	v_fmac_f32_dpp v212, v204, v124 row_ror:1 row_mask:0xf bank_mask:0xf bound_ctrl:1
	v_fmac_f32_dpp v213, v205, v125 row_ror:1 row_mask:0xf bank_mask:0xf bound_ctrl:1
	v_fmac_f32_dpp v220, v208, v140 row_ror:1 row_mask:0xf bank_mask:0xf bound_ctrl:1
	v_fmac_f32_dpp v221, v209, v141 row_ror:1 row_mask:0xf bank_mask:0xf bound_ctrl:1
	v_cndmask_b32_e64 v204, v92, v84, s[34:35]
	v_cndmask_b32_e64 v205, v93, v85, s[34:35]
	v_cndmask_b32_e64 v208, v88, v80, s[34:35]
	v_cndmask_b32_e64 v209, v89, v81, s[34:35]
	v_fmac_f32_dpp v212, v204, v132 row_ror:15 row_mask:0xf bank_mask:0xf
	v_fmac_f32_dpp v213, v205, v133 row_ror:15 row_mask:0xf bank_mask:0xf
	v_fmac_f32_dpp v220, v208, v148 row_ror:15 row_mask:0xf bank_mask:0xf
	v_fmac_f32_dpp v221, v209, v149 row_ror:15 row_mask:0xf bank_mask:0xf
	v_pk_mul_f32 v[222:223], v[254:255], v[212:213]
	v_exp_f32_e32 v222, v222
	v_exp_f32_e32 v223, v223
	s_nop 0
	v_pk_add_f32 v[222:223], v[222:223], v[252:253]
	v_rcp_f32_e32 v222, v222
	v_rcp_f32_e32 v223, v223
	s_nop 0
	v_pk_mul_f32 v[212:213], v[212:213], v[222:223]
	v_pk_mul_f32 v[220:221], v[220:221], v[212:213]
	s_nop 0
	s_nop 0
	v_cndmask_b32_e64 v210, v94, 0, vcc
	v_cndmask_b32_e64 v211, v95, 0, vcc
	v_cndmask_b32_e64 v214, v90, 0, vcc
	v_cndmask_b32_e64 v215, v91, 0, vcc
	v_pk_fma_f32 v[206:207], v[94:95], v[130:131], v[138:139]
	v_pk_fma_f32 v[244:245], v[90:91], v[146:147], v[154:155]
	v_fmac_f32_dpp v206, v210, v126 row_ror:1 row_mask:0xf bank_mask:0xf bound_ctrl:1
	v_fmac_f32_dpp v207, v211, v127 row_ror:1 row_mask:0xf bank_mask:0xf bound_ctrl:1
	v_fmac_f32_dpp v244, v214, v142 row_ror:1 row_mask:0xf bank_mask:0xf bound_ctrl:1
	v_fmac_f32_dpp v245, v215, v143 row_ror:1 row_mask:0xf bank_mask:0xf bound_ctrl:1
	v_cndmask_b32_e64 v210, v94, v86, s[34:35]
	v_cndmask_b32_e64 v211, v95, v87, s[34:35]
	v_cndmask_b32_e64 v214, v90, v82, s[34:35]
	v_cndmask_b32_e64 v215, v91, v83, s[34:35]
	v_fmac_f32_dpp v206, v210, v134 row_ror:15 row_mask:0xf bank_mask:0xf
	v_fmac_f32_dpp v207, v211, v135 row_ror:15 row_mask:0xf bank_mask:0xf
	v_fmac_f32_dpp v244, v214, v150 row_ror:15 row_mask:0xf bank_mask:0xf
	v_fmac_f32_dpp v245, v215, v151 row_ror:15 row_mask:0xf bank_mask:0xf
	v_pk_mul_f32 v[250:251], v[254:255], v[206:207]
	v_exp_f32_e32 v250, v250
	v_exp_f32_e32 v251, v251
	s_nop 0
	v_pk_add_f32 v[250:251], v[250:251], v[252:253]
	v_rcp_f32_e32 v250, v250
	v_rcp_f32_e32 v251, v251
	s_nop 0
	v_pk_mul_f32 v[206:207], v[206:207], v[250:251]
	v_pk_mul_f32 v[244:245], v[244:245], v[206:207]
	s_nop 0
	s_nop 0
	s_add_i32 s85, s31, 0x80
	s_ashr_i32 s10, s85, 6
	s_ashr_i32 s11, s10, 31
	s_lshl_b64 s[10:11], s[10:11], 2
	v_or_b32_e32 v156, s10, v200
	v_cvt_pk_bf16_f32 v96, v220, v221
	v_cvt_pk_bf16_f32 v97, v244, v245
	s_and_saveexec_b64 s[40:41], s[36:37]
	s_cbranch_execz .LBB0_1411
	v_mov_b64_e32 v[98:99], s[0:1]
	v_mad_i64_i32 v[98:99], s[86:87], v156, s66, v[98:99]
	v_lshl_add_u64 v[98:99], s[16:17], 1, v[98:99]
	s_lshl_b32 s48, s5, 1
	v_lshl_add_u64 v[98:99], v[98:99], 0, s[48:49]
	v_mov_b32_e32 v179, v165
	v_lshl_add_u64 v[98:99], v[98:99], 0, v[178:179]
	v_cvt_pk_bf16_f32 v100, v92, v93
	v_cvt_pk_bf16_f32 v101, v94, v95
	global_store_dwordx2 v[98:99], v[100:101], off
	v_cvt_pk_bf16_f32 v100, v88, v89
	v_cvt_pk_bf16_f32 v101, v90, v91
	global_store_dwordx2 v[98:99], v[100:101], off offset:256
.LBB0_1411:
	s_or_b64 exec, exec, s[40:41]
	v_cndmask_b32_e64 v240, v84, v92, vcc
	v_cndmask_b32_e64 v241, v85, v93, vcc
	v_cndmask_b32_e64 v248, v80, v88, vcc
	v_cndmask_b32_e64 v249, v81, v89, vcc
	v_pk_fma_f32 v[242:243], v[84:85], v[128:129], v[136:137]
	v_pk_fma_f32 v[246:247], v[80:81], v[144:145], v[152:153]
	v_fmac_f32_dpp v242, v240, v124 row_ror:1 row_mask:0xf bank_mask:0xf bound_ctrl:1
	v_fmac_f32_dpp v243, v241, v125 row_ror:1 row_mask:0xf bank_mask:0xf bound_ctrl:1
	v_fmac_f32_dpp v246, v248, v140 row_ror:1 row_mask:0xf bank_mask:0xf bound_ctrl:1
	v_fmac_f32_dpp v247, v249, v141 row_ror:1 row_mask:0xf bank_mask:0xf bound_ctrl:1
	v_cndmask_b32_e64 v240, v84, v76, s[34:35]
	v_cndmask_b32_e64 v241, v85, v77, s[34:35]
	v_cndmask_b32_e64 v248, v80, v72, s[34:35]
	v_cndmask_b32_e64 v249, v81, v73, s[34:35]
	v_fmac_f32_dpp v242, v240, v132 row_ror:15 row_mask:0xf bank_mask:0xf
	v_fmac_f32_dpp v243, v241, v133 row_ror:15 row_mask:0xf bank_mask:0xf
	v_fmac_f32_dpp v246, v248, v148 row_ror:15 row_mask:0xf bank_mask:0xf
	v_fmac_f32_dpp v247, v249, v149 row_ror:15 row_mask:0xf bank_mask:0xf
	v_pk_mul_f32 v[204:205], v[254:255], v[242:243]
	v_exp_f32_e32 v204, v204
	v_exp_f32_e32 v205, v205
	s_nop 0
	v_pk_add_f32 v[204:205], v[204:205], v[252:253]
	v_rcp_f32_e32 v204, v204
	v_rcp_f32_e32 v205, v205
	s_nop 0
	v_pk_mul_f32 v[242:243], v[242:243], v[204:205]
	v_pk_mul_f32 v[246:247], v[246:247], v[242:243]
	s_nop 0
	s_nop 0
	s_nop 0
	s_nop 0
	s_nop 0
	v_cndmask_b32_e64 v208, v86, v94, vcc
	v_cndmask_b32_e64 v209, v87, v95, vcc
	v_cndmask_b32_e64 v212, v82, v90, vcc
	v_cndmask_b32_e64 v213, v83, v91, vcc
	v_pk_fma_f32 v[222:223], v[86:87], v[130:131], v[138:139]
	v_pk_fma_f32 v[210:211], v[82:83], v[146:147], v[154:155]
	v_fmac_f32_dpp v222, v208, v126 row_ror:1 row_mask:0xf bank_mask:0xf bound_ctrl:1
	v_fmac_f32_dpp v223, v209, v127 row_ror:1 row_mask:0xf bank_mask:0xf bound_ctrl:1
	v_fmac_f32_dpp v210, v212, v142 row_ror:1 row_mask:0xf bank_mask:0xf bound_ctrl:1
	v_fmac_f32_dpp v211, v213, v143 row_ror:1 row_mask:0xf bank_mask:0xf bound_ctrl:1
	v_cndmask_b32_e64 v208, v86, v78, s[34:35]
	v_cndmask_b32_e64 v209, v87, v79, s[34:35]
	v_cndmask_b32_e64 v212, v82, v74, s[34:35]
	v_cndmask_b32_e64 v213, v83, v75, s[34:35]
	v_fmac_f32_dpp v222, v208, v134 row_ror:15 row_mask:0xf bank_mask:0xf
	v_fmac_f32_dpp v223, v209, v135 row_ror:15 row_mask:0xf bank_mask:0xf
	v_fmac_f32_dpp v210, v212, v150 row_ror:15 row_mask:0xf bank_mask:0xf
	v_fmac_f32_dpp v211, v213, v151 row_ror:15 row_mask:0xf bank_mask:0xf
	v_pk_mul_f32 v[214:215], v[254:255], v[222:223]
	v_exp_f32_e32 v214, v214
	v_exp_f32_e32 v215, v215
	s_nop 0
	v_pk_add_f32 v[214:215], v[214:215], v[252:253]
	v_rcp_f32_e32 v214, v214
	v_rcp_f32_e32 v215, v215
	s_nop 0
	v_pk_mul_f32 v[222:223], v[222:223], v[214:215]
	v_pk_mul_f32 v[210:211], v[210:211], v[222:223]
	s_nop 0
	s_nop 0
	s_nop 0
	s_nop 0
	v_cndmask_b32_e64 v206, v76, v84, vcc
	v_cndmask_b32_e64 v207, v77, v85, vcc
	v_cndmask_b32_e64 v250, v72, v80, vcc
	v_cndmask_b32_e64 v251, v73, v81, vcc
	v_pk_fma_f32 v[220:221], v[76:77], v[128:129], v[136:137]
	v_pk_fma_f32 v[244:245], v[72:73], v[144:145], v[152:153]
	v_fmac_f32_dpp v220, v206, v124 row_ror:1 row_mask:0xf bank_mask:0xf bound_ctrl:1
	v_fmac_f32_dpp v221, v207, v125 row_ror:1 row_mask:0xf bank_mask:0xf bound_ctrl:1
	v_fmac_f32_dpp v244, v250, v140 row_ror:1 row_mask:0xf bank_mask:0xf bound_ctrl:1
	v_fmac_f32_dpp v245, v251, v141 row_ror:1 row_mask:0xf bank_mask:0xf bound_ctrl:1
	v_cndmask_b32_e64 v206, v76, v68, s[34:35]
	v_cndmask_b32_e64 v207, v77, v69, s[34:35]
	v_cndmask_b32_e64 v250, v72, v64, s[34:35]
	v_cndmask_b32_e64 v251, v73, v65, s[34:35]
	v_fmac_f32_dpp v220, v206, v132 row_ror:15 row_mask:0xf bank_mask:0xf
	v_fmac_f32_dpp v221, v207, v133 row_ror:15 row_mask:0xf bank_mask:0xf
	v_fmac_f32_dpp v244, v250, v148 row_ror:15 row_mask:0xf bank_mask:0xf
	v_fmac_f32_dpp v245, v251, v149 row_ror:15 row_mask:0xf bank_mask:0xf
	v_pk_mul_f32 v[240:241], v[254:255], v[220:221]
	v_exp_f32_e32 v240, v240
	v_exp_f32_e32 v241, v241
	s_nop 0
	v_pk_add_f32 v[240:241], v[240:241], v[252:253]
	v_rcp_f32_e32 v240, v240
	v_rcp_f32_e32 v241, v241
	s_nop 0
	v_pk_mul_f32 v[220:221], v[220:221], v[240:241]
	v_pk_mul_f32 v[244:245], v[244:245], v[220:221]
	v_cvt_pk_bf16_f32 v88, v246, v247
	v_cvt_pk_bf16_f32 v89, v210, v211
	s_nop 0
	s_nop 0
	s_nop 0
	s_nop 0
	v_cndmask_b32_e64 v248, v78, v86, vcc
	v_cndmask_b32_e64 v249, v79, v87, vcc
	v_cndmask_b32_e64 v242, v74, v82, vcc
	v_cndmask_b32_e64 v243, v75, v83, vcc
	v_pk_fma_f32 v[204:205], v[78:79], v[130:131], v[138:139]
	v_pk_fma_f32 v[208:209], v[74:75], v[146:147], v[154:155]
	v_fmac_f32_dpp v204, v248, v126 row_ror:1 row_mask:0xf bank_mask:0xf bound_ctrl:1
	v_fmac_f32_dpp v205, v249, v127 row_ror:1 row_mask:0xf bank_mask:0xf bound_ctrl:1
	v_fmac_f32_dpp v208, v242, v142 row_ror:1 row_mask:0xf bank_mask:0xf bound_ctrl:1
	v_fmac_f32_dpp v209, v243, v143 row_ror:1 row_mask:0xf bank_mask:0xf bound_ctrl:1
	v_cndmask_b32_e64 v248, v78, v70, s[34:35]
	v_cndmask_b32_e64 v249, v79, v71, s[34:35]
	v_cndmask_b32_e64 v242, v74, v66, s[34:35]
	v_cndmask_b32_e64 v243, v75, v67, s[34:35]
	v_fmac_f32_dpp v204, v248, v134 row_ror:15 row_mask:0xf bank_mask:0xf
	v_fmac_f32_dpp v205, v249, v135 row_ror:15 row_mask:0xf bank_mask:0xf
	v_fmac_f32_dpp v208, v242, v150 row_ror:15 row_mask:0xf bank_mask:0xf
	v_fmac_f32_dpp v209, v243, v151 row_ror:15 row_mask:0xf bank_mask:0xf
	v_pk_mul_f32 v[212:213], v[254:255], v[204:205]
	v_exp_f32_e32 v212, v212
	v_exp_f32_e32 v213, v213
	s_nop 0
	v_pk_add_f32 v[212:213], v[212:213], v[252:253]
	v_rcp_f32_e32 v212, v212
	v_rcp_f32_e32 v213, v213
	s_nop 0
	v_pk_mul_f32 v[204:205], v[204:205], v[212:213]
	v_pk_mul_f32 v[208:209], v[208:209], v[204:205]
	s_nop 0
	s_nop 0
	s_nop 0
	s_nop 0
	v_cndmask_b32_e64 v222, v68, v76, vcc
	v_cndmask_b32_e64 v223, v69, v77, vcc
	v_cndmask_b32_e64 v214, v64, v72, vcc
	v_cndmask_b32_e64 v215, v65, v73, vcc
	v_pk_fma_f32 v[206:207], v[68:69], v[128:129], v[136:137]
	v_pk_fma_f32 v[250:251], v[64:65], v[144:145], v[152:153]
	v_fmac_f32_dpp v206, v222, v124 row_ror:1 row_mask:0xf bank_mask:0xf bound_ctrl:1
	v_fmac_f32_dpp v207, v223, v125 row_ror:1 row_mask:0xf bank_mask:0xf bound_ctrl:1
	v_fmac_f32_dpp v250, v214, v140 row_ror:1 row_mask:0xf bank_mask:0xf bound_ctrl:1
	v_fmac_f32_dpp v251, v215, v141 row_ror:1 row_mask:0xf bank_mask:0xf bound_ctrl:1
	v_cndmask_b32_e64 v222, v68, 0, s[34:35]
	v_cndmask_b32_e64 v223, v69, 0, s[34:35]
	v_cndmask_b32_e64 v214, v64, 0, s[34:35]
	v_cndmask_b32_e64 v215, v65, 0, s[34:35]
	v_fmac_f32_dpp v206, v222, v132 row_ror:15 row_mask:0xf bank_mask:0xf
	v_fmac_f32_dpp v207, v223, v133 row_ror:15 row_mask:0xf bank_mask:0xf
	v_fmac_f32_dpp v250, v214, v148 row_ror:15 row_mask:0xf bank_mask:0xf
	v_fmac_f32_dpp v251, v215, v149 row_ror:15 row_mask:0xf bank_mask:0xf
	v_pk_mul_f32 v[220:221], v[254:255], v[206:207]
	v_exp_f32_e32 v220, v220
	v_exp_f32_e32 v221, v221
	s_nop 0
	v_pk_add_f32 v[220:221], v[220:221], v[252:253]
	v_rcp_f32_e32 v220, v220
	v_rcp_f32_e32 v221, v221
	s_nop 0
	v_pk_mul_f32 v[206:207], v[206:207], v[220:221]
	v_pk_mul_f32 v[250:251], v[250:251], v[206:207]
	v_cvt_pk_bf16_f32 v80, v244, v245
	v_cvt_pk_bf16_f32 v81, v208, v209
	s_nop 0
	s_nop 0
	s_nop 0
	s_nop 0
	v_cndmask_b32_e64 v240, v70, v78, vcc
	v_cndmask_b32_e64 v241, v71, v79, vcc
	v_cndmask_b32_e64 v246, v66, v74, vcc
	v_cndmask_b32_e64 v247, v67, v75, vcc
	v_pk_fma_f32 v[210:211], v[70:71], v[130:131], v[138:139]
	v_pk_fma_f32 v[248:249], v[66:67], v[146:147], v[154:155]
	v_fmac_f32_dpp v210, v240, v126 row_ror:1 row_mask:0xf bank_mask:0xf bound_ctrl:1
	v_fmac_f32_dpp v211, v241, v127 row_ror:1 row_mask:0xf bank_mask:0xf bound_ctrl:1
	v_fmac_f32_dpp v248, v246, v142 row_ror:1 row_mask:0xf bank_mask:0xf bound_ctrl:1
	v_fmac_f32_dpp v249, v247, v143 row_ror:1 row_mask:0xf bank_mask:0xf bound_ctrl:1
	v_cndmask_b32_e64 v240, v70, 0, s[34:35]
	v_cndmask_b32_e64 v241, v71, 0, s[34:35]
	v_cndmask_b32_e64 v246, v66, 0, s[34:35]
	v_cndmask_b32_e64 v247, v67, 0, s[34:35]
	v_fmac_f32_dpp v210, v240, v134 row_ror:15 row_mask:0xf bank_mask:0xf
	v_fmac_f32_dpp v211, v241, v135 row_ror:15 row_mask:0xf bank_mask:0xf
	v_fmac_f32_dpp v248, v246, v150 row_ror:15 row_mask:0xf bank_mask:0xf
	v_fmac_f32_dpp v249, v247, v151 row_ror:15 row_mask:0xf bank_mask:0xf
	v_pk_mul_f32 v[242:243], v[254:255], v[210:211]
	v_exp_f32_e32 v242, v242
	v_exp_f32_e32 v243, v243
	s_nop 0
	v_pk_add_f32 v[242:243], v[242:243], v[252:253]
	v_rcp_f32_e32 v242, v242
	v_rcp_f32_e32 v243, v243
	s_nop 0
	v_pk_mul_f32 v[210:211], v[210:211], v[242:243]
	v_pk_mul_f32 v[248:249], v[248:249], v[210:211]
	s_nop 0
	s_nop 0
	s_nop 0
	s_nop 0
	v_cvt_pk_bf16_f32 v72, v250, v251
	v_cvt_pk_bf16_f32 v73, v248, v249
	s_and_saveexec_b64 s[40:41], s[38:39]
	s_cbranch_execz .LBB0_1413
	v_mov_b32_e32 v181, v165
	v_lshl_add_u64 v[74:75], s[10:11], 0, v[180:181]
	v_mov_b64_e32 v[76:77], s[0:1]
	s_movk_i32 s48, 0x2c00
	v_mad_u64_u32 v[76:77], s[86:87], v74, s48, v[76:77]
	v_mad_i32_i24 v77, v75, s48, v77
	v_lshl_add_u64 v[74:75], s[16:17], 1, v[76:77]
	s_lshl_b32 s48, s5, 1
	v_lshl_add_u64 v[74:75], v[74:75], 0, s[48:49]
	v_mov_b32_e32 v179, v165
	s_movk_i32 s66, 0x2c00
	v_lshl_add_u64 v[74:75], v[74:75], 0, v[178:179]
	v_cvt_pk_bf16_f32 v68, v68, v69
	v_cvt_pk_bf16_f32 v69, v70, v71
	global_store_dwordx2 v[74:75], v[68:69], off
	v_cvt_pk_bf16_f32 v64, v64, v65
	v_cvt_pk_bf16_f32 v65, v66, v67
	global_store_dwordx2 v[74:75], v[64:65], off offset:256
.LBB0_1413:
	s_or_b64 exec, exec, s[40:41]
	v_or_b32_e32 v68, 4, v182
	v_ashrrev_i32_e32 v69, 31, v68
	v_lshlrev_b64 v[82:83], 2, v[68:69]
	global_load_dwordx4 v[64:67], v[184:185], off offset:16
	v_lshl_add_u64 v[68:69], s[58:59], 0, v[82:83]
	global_load_dwordx4 v[68:71], v[68:69], off
	v_lshl_add_u64 v[74:75], s[60:61], 0, v[82:83]
	global_load_dwordx4 v[74:77], v[74:75], off
	s_nop 0
	global_load_dwordx4 v[84:87], v[186:187], off offset:16
	v_lshl_add_u64 v[90:91], s[12:13], 0, v[82:83]
	global_load_dwordx4 v[92:95], v[90:91], off
	v_lshl_add_u64 v[90:91], s[50:51], 0, v[82:83]
	global_load_dwordx4 v[100:103], v[90:91], off
	v_lshl_add_u64 v[90:91], s[20:21], 0, v[82:83]
	global_load_dwordx4 v[108:111], v[90:91], off
	v_lshl_add_u64 v[82:83], s[44:45], 0, v[82:83]
	global_load_dwordx4 v[122:125], v[82:83], off
	s_nop 0
	v_mov_b32_e32 v106, v165
	s_ashr_i32 s40, s6, 6
	s_ashr_i32 s41, s40, 31
	s_ashr_i32 s31, s31, 8
	s_lshl_b64 s[40:41], s[40:41], 15
	v_or_b32_e32 v78, s7, v200
	v_mov_b32_e32 v107, v165
	s_add_u32 s86, s80, s40
	s_mul_hi_i32 s7, s31, 0x160000
	s_mul_i32 s31, s31, 0x160000
	v_and_b32_e32 v82, 56, v182
	v_lshlrev_b32_e32 v78, 6, v78
	s_movk_i32 s6, 0x33c0
	s_addc_u32 s87, s81, s41
	v_and_or_b32 v78, v78, s6, v82
	s_add_u32 s40, s86, s31
	s_addc_u32 s41, s87, s7
	v_lshlrev_b32_e32 v164, 1, v78
	s_waitcnt vmcnt(0)
	v_cndmask_b32_e64 v204, v60, 0, vcc
	v_cndmask_b32_e64 v205, v61, 0, vcc
	v_cndmask_b32_e64 v212, v56, 0, vcc
	v_cndmask_b32_e64 v213, v57, 0, vcc
	v_pk_fma_f32 v[222:223], v[60:61], v[68:69], v[84:85]
	v_pk_fma_f32 v[214:215], v[56:57], v[100:101], v[122:123]
	v_fmac_f32_dpp v222, v204, v64 row_ror:1 row_mask:0xf bank_mask:0xf bound_ctrl:1
	v_fmac_f32_dpp v223, v205, v65 row_ror:1 row_mask:0xf bank_mask:0xf bound_ctrl:1
	v_fmac_f32_dpp v214, v212, v92 row_ror:1 row_mask:0xf bank_mask:0xf bound_ctrl:1
	v_fmac_f32_dpp v215, v213, v93 row_ror:1 row_mask:0xf bank_mask:0xf bound_ctrl:1
	v_cndmask_b32_e64 v204, v60, v52, s[34:35]
	v_cndmask_b32_e64 v205, v61, v53, s[34:35]
	v_cndmask_b32_e64 v212, v56, v48, s[34:35]
	v_cndmask_b32_e64 v213, v57, v49, s[34:35]
	v_fmac_f32_dpp v222, v204, v74 row_ror:15 row_mask:0xf bank_mask:0xf
	v_fmac_f32_dpp v223, v205, v75 row_ror:15 row_mask:0xf bank_mask:0xf
	v_fmac_f32_dpp v214, v212, v108 row_ror:15 row_mask:0xf bank_mask:0xf
	v_fmac_f32_dpp v215, v213, v109 row_ror:15 row_mask:0xf bank_mask:0xf
	v_pk_mul_f32 v[206:207], v[254:255], v[222:223]
	v_exp_f32_e32 v206, v206
	v_exp_f32_e32 v207, v207
	s_nop 0
	v_pk_add_f32 v[206:207], v[206:207], v[252:253]
	v_rcp_f32_e32 v206, v206
	v_rcp_f32_e32 v207, v207
	s_nop 0
	v_pk_mul_f32 v[222:223], v[222:223], v[206:207]
	v_pk_mul_f32 v[214:215], v[214:215], v[222:223]
	v_cndmask_b32_e64 v220, v62, 0, vcc
	v_cndmask_b32_e64 v221, v63, 0, vcc
	v_cndmask_b32_e64 v244, v58, 0, vcc
	v_cndmask_b32_e64 v245, v59, 0, vcc
	v_pk_fma_f32 v[208:209], v[62:63], v[70:71], v[86:87]
	v_pk_fma_f32 v[240:241], v[58:59], v[102:103], v[124:125]
	v_fmac_f32_dpp v208, v220, v66 row_ror:1 row_mask:0xf bank_mask:0xf bound_ctrl:1
	v_fmac_f32_dpp v209, v221, v67 row_ror:1 row_mask:0xf bank_mask:0xf bound_ctrl:1
	v_fmac_f32_dpp v240, v244, v94 row_ror:1 row_mask:0xf bank_mask:0xf bound_ctrl:1
	v_fmac_f32_dpp v241, v245, v95 row_ror:1 row_mask:0xf bank_mask:0xf bound_ctrl:1
	v_cndmask_b32_e64 v220, v62, v54, s[34:35]
	v_cndmask_b32_e64 v221, v63, v55, s[34:35]
	v_cndmask_b32_e64 v244, v58, v50, s[34:35]
	v_cndmask_b32_e64 v245, v59, v51, s[34:35]
	v_fmac_f32_dpp v208, v220, v76 row_ror:15 row_mask:0xf bank_mask:0xf
	v_fmac_f32_dpp v209, v221, v77 row_ror:15 row_mask:0xf bank_mask:0xf
	v_fmac_f32_dpp v240, v244, v110 row_ror:15 row_mask:0xf bank_mask:0xf
	v_fmac_f32_dpp v241, v245, v111 row_ror:15 row_mask:0xf bank_mask:0xf
	v_pk_mul_f32 v[246:247], v[254:255], v[208:209]
	v_exp_f32_e32 v246, v246
	v_exp_f32_e32 v247, v247
	s_nop 0
	v_pk_add_f32 v[246:247], v[246:247], v[252:253]
	v_rcp_f32_e32 v246, v246
	v_rcp_f32_e32 v247, v247
	s_nop 0
	v_pk_mul_f32 v[208:209], v[208:209], v[246:247]
	v_pk_mul_f32 v[240:241], v[240:241], v[208:209]
	s_nop 1
	s_nop 0
	v_cvt_pk_bf16_f32 v120, v214, v215
	v_cvt_pk_bf16_f32 v121, v240, v241
	global_store_dwordx4 v164, v[118:121], s[40:41]
	s_and_saveexec_b64 s[6:7], s[36:37]
	s_cbranch_execz .LBB0_1415
	v_mov_b64_e32 v[78:79], s[0:1]
	v_mad_i64_i32 v[78:79], s[88:89], v183, s66, v[78:79]
	v_lshl_add_u64 v[78:79], s[16:17], 1, v[78:79]
	s_lshl_b32 s48, s5, 1
	v_lshl_add_u64 v[78:79], v[78:79], 0, s[48:49]
	v_mov_b32_e32 v179, v165
	v_lshl_add_u64 v[78:79], v[78:79], 0, v[178:179]
	v_cvt_pk_bf16_f32 v90, v60, v61
	v_cvt_pk_bf16_f32 v91, v62, v63
	global_store_dwordx2 v[78:79], v[90:91], off offset:8
	v_cvt_pk_bf16_f32 v90, v56, v57
	v_cvt_pk_bf16_f32 v91, v58, v59
	global_store_dwordx2 v[78:79], v[90:91], off offset:264
.LBB0_1415:
	s_or_b64 exec, exec, s[6:7]
	v_cndmask_b32_e64 v210, v52, v60, vcc
	v_cndmask_b32_e64 v211, v53, v61, vcc
	v_cndmask_b32_e64 v242, v48, v56, vcc
	v_cndmask_b32_e64 v243, v49, v57, vcc
	v_pk_fma_f32 v[250:251], v[52:53], v[68:69], v[84:85]
	v_pk_fma_f32 v[248:249], v[48:49], v[100:101], v[122:123]
	v_fmac_f32_dpp v250, v210, v64 row_ror:1 row_mask:0xf bank_mask:0xf bound_ctrl:1
	v_fmac_f32_dpp v251, v211, v65 row_ror:1 row_mask:0xf bank_mask:0xf bound_ctrl:1
	v_fmac_f32_dpp v248, v242, v92 row_ror:1 row_mask:0xf bank_mask:0xf bound_ctrl:1
	v_fmac_f32_dpp v249, v243, v93 row_ror:1 row_mask:0xf bank_mask:0xf bound_ctrl:1
	v_cndmask_b32_e64 v210, v52, v44, s[34:35]
	v_cndmask_b32_e64 v211, v53, v45, s[34:35]
	v_cndmask_b32_e64 v242, v48, v40, s[34:35]
	v_cndmask_b32_e64 v243, v49, v41, s[34:35]
	v_fmac_f32_dpp v250, v210, v74 row_ror:15 row_mask:0xf bank_mask:0xf
	v_fmac_f32_dpp v251, v211, v75 row_ror:15 row_mask:0xf bank_mask:0xf
	v_fmac_f32_dpp v248, v242, v108 row_ror:15 row_mask:0xf bank_mask:0xf
	v_fmac_f32_dpp v249, v243, v109 row_ror:15 row_mask:0xf bank_mask:0xf
	v_pk_mul_f32 v[204:205], v[254:255], v[250:251]
	v_exp_f32_e32 v204, v204
	v_exp_f32_e32 v205, v205
	s_nop 0
	v_pk_add_f32 v[204:205], v[204:205], v[252:253]
	v_rcp_f32_e32 v204, v204
	v_rcp_f32_e32 v205, v205
	s_nop 0
	v_pk_mul_f32 v[250:251], v[250:251], v[204:205]
	v_pk_mul_f32 v[248:249], v[248:249], v[250:251]
	s_nop 0
	s_nop 0
	s_nop 0
	s_nop 0
	s_nop 0
	v_cndmask_b32_e64 v212, v54, v62, vcc
	v_cndmask_b32_e64 v213, v55, v63, vcc
	v_cndmask_b32_e64 v222, v50, v58, vcc
	v_cndmask_b32_e64 v223, v51, v59, vcc
	v_pk_fma_f32 v[206:207], v[54:55], v[70:71], v[86:87]
	v_pk_fma_f32 v[220:221], v[50:51], v[102:103], v[124:125]
	v_fmac_f32_dpp v206, v212, v66 row_ror:1 row_mask:0xf bank_mask:0xf bound_ctrl:1
	v_fmac_f32_dpp v207, v213, v67 row_ror:1 row_mask:0xf bank_mask:0xf bound_ctrl:1
	v_fmac_f32_dpp v220, v222, v94 row_ror:1 row_mask:0xf bank_mask:0xf bound_ctrl:1
	v_fmac_f32_dpp v221, v223, v95 row_ror:1 row_mask:0xf bank_mask:0xf bound_ctrl:1
	v_cndmask_b32_e64 v212, v54, v46, s[34:35]
	v_cndmask_b32_e64 v213, v55, v47, s[34:35]
	v_cndmask_b32_e64 v222, v50, v42, s[34:35]
	v_cndmask_b32_e64 v223, v51, v43, s[34:35]
	v_fmac_f32_dpp v206, v212, v76 row_ror:15 row_mask:0xf bank_mask:0xf
	v_fmac_f32_dpp v207, v213, v77 row_ror:15 row_mask:0xf bank_mask:0xf
	v_fmac_f32_dpp v220, v222, v110 row_ror:15 row_mask:0xf bank_mask:0xf
	v_fmac_f32_dpp v221, v223, v111 row_ror:15 row_mask:0xf bank_mask:0xf
	v_pk_mul_f32 v[244:245], v[254:255], v[206:207]
	v_exp_f32_e32 v244, v244
	v_exp_f32_e32 v245, v245
	s_nop 0
	v_pk_add_f32 v[244:245], v[244:245], v[252:253]
	v_rcp_f32_e32 v244, v244
	v_rcp_f32_e32 v245, v245
	s_nop 0
	v_pk_mul_f32 v[206:207], v[206:207], v[244:245]
	v_pk_mul_f32 v[220:221], v[220:221], v[206:207]
	s_nop 0
	v_cndmask_b32_e64 v208, v44, v52, vcc
	v_cndmask_b32_e64 v209, v45, v53, vcc
	v_cndmask_b32_e64 v246, v40, v48, vcc
	v_cndmask_b32_e64 v247, v41, v49, vcc
	v_pk_fma_f32 v[214:215], v[44:45], v[68:69], v[84:85]
	v_pk_fma_f32 v[240:241], v[40:41], v[100:101], v[122:123]
	v_fmac_f32_dpp v214, v208, v64 row_ror:1 row_mask:0xf bank_mask:0xf bound_ctrl:1
	v_fmac_f32_dpp v215, v209, v65 row_ror:1 row_mask:0xf bank_mask:0xf bound_ctrl:1
	v_fmac_f32_dpp v240, v246, v92 row_ror:1 row_mask:0xf bank_mask:0xf bound_ctrl:1
	v_fmac_f32_dpp v241, v247, v93 row_ror:1 row_mask:0xf bank_mask:0xf bound_ctrl:1
	v_cndmask_b32_e64 v208, v44, v36, s[34:35]
	v_cndmask_b32_e64 v209, v45, v37, s[34:35]
	v_cndmask_b32_e64 v246, v40, v32, s[34:35]
	v_cndmask_b32_e64 v247, v41, v33, s[34:35]
	v_fmac_f32_dpp v214, v208, v74 row_ror:15 row_mask:0xf bank_mask:0xf
	v_fmac_f32_dpp v215, v209, v75 row_ror:15 row_mask:0xf bank_mask:0xf
	v_fmac_f32_dpp v240, v246, v108 row_ror:15 row_mask:0xf bank_mask:0xf
	v_fmac_f32_dpp v241, v247, v109 row_ror:15 row_mask:0xf bank_mask:0xf
	v_pk_mul_f32 v[210:211], v[254:255], v[214:215]
	v_exp_f32_e32 v210, v210
	v_exp_f32_e32 v211, v211
	s_nop 0
	v_pk_add_f32 v[210:211], v[210:211], v[252:253]
	v_rcp_f32_e32 v210, v210
	v_rcp_f32_e32 v211, v211
	s_nop 0
	v_pk_mul_f32 v[214:215], v[214:215], v[210:211]
	v_pk_mul_f32 v[240:241], v[240:241], v[214:215]
	s_nop 0
	s_nop 0
	s_nop 0
	v_cvt_pk_bf16_f32 v118, v248, v249
	s_nop 0
	s_nop 0
	v_cvt_pk_bf16_f32 v119, v220, v221
	s_nop 0
	v_cndmask_b32_e64 v242, v46, v54, vcc
	v_cndmask_b32_e64 v243, v47, v55, vcc
	v_cndmask_b32_e64 v250, v42, v50, vcc
	v_cndmask_b32_e64 v251, v43, v51, vcc
	v_pk_fma_f32 v[204:205], v[46:47], v[70:71], v[86:87]
	v_pk_fma_f32 v[212:213], v[42:43], v[102:103], v[124:125]
	v_fmac_f32_dpp v204, v242, v66 row_ror:1 row_mask:0xf bank_mask:0xf bound_ctrl:1
	v_fmac_f32_dpp v205, v243, v67 row_ror:1 row_mask:0xf bank_mask:0xf bound_ctrl:1
	v_fmac_f32_dpp v212, v250, v94 row_ror:1 row_mask:0xf bank_mask:0xf bound_ctrl:1
	v_fmac_f32_dpp v213, v251, v95 row_ror:1 row_mask:0xf bank_mask:0xf bound_ctrl:1
	v_cndmask_b32_e64 v242, v46, v38, s[34:35]
	v_cndmask_b32_e64 v243, v47, v39, s[34:35]
	v_cndmask_b32_e64 v250, v42, v34, s[34:35]
	v_cndmask_b32_e64 v251, v43, v35, s[34:35]
	v_fmac_f32_dpp v204, v242, v76 row_ror:15 row_mask:0xf bank_mask:0xf
	v_fmac_f32_dpp v205, v243, v77 row_ror:15 row_mask:0xf bank_mask:0xf
	v_fmac_f32_dpp v212, v250, v110 row_ror:15 row_mask:0xf bank_mask:0xf
	v_fmac_f32_dpp v213, v251, v111 row_ror:15 row_mask:0xf bank_mask:0xf
	v_pk_mul_f32 v[222:223], v[254:255], v[204:205]
	v_exp_f32_e32 v222, v222
	v_exp_f32_e32 v223, v223
	s_nop 0
	v_pk_add_f32 v[222:223], v[222:223], v[252:253]
	v_rcp_f32_e32 v222, v222
	v_rcp_f32_e32 v223, v223
	s_nop 0
	v_pk_mul_f32 v[204:205], v[204:205], v[222:223]
	v_pk_mul_f32 v[212:213], v[212:213], v[204:205]
	s_nop 0
	s_nop 0
	v_cndmask_b32_e64 v206, v36, v44, vcc
	v_cndmask_b32_e64 v207, v37, v45, vcc
	v_cndmask_b32_e64 v244, v32, v40, vcc
	v_cndmask_b32_e64 v245, v33, v41, vcc
	v_pk_fma_f32 v[208:209], v[36:37], v[68:69], v[84:85]
	v_pk_fma_f32 v[246:247], v[32:33], v[100:101], v[122:123]
	v_fmac_f32_dpp v208, v206, v64 row_ror:1 row_mask:0xf bank_mask:0xf bound_ctrl:1
	v_fmac_f32_dpp v209, v207, v65 row_ror:1 row_mask:0xf bank_mask:0xf bound_ctrl:1
	v_fmac_f32_dpp v246, v244, v92 row_ror:1 row_mask:0xf bank_mask:0xf bound_ctrl:1
	v_fmac_f32_dpp v247, v245, v93 row_ror:1 row_mask:0xf bank_mask:0xf bound_ctrl:1
	v_cndmask_b32_e64 v206, v36, 0, s[34:35]
	v_cndmask_b32_e64 v207, v37, 0, s[34:35]
	v_cndmask_b32_e64 v244, v32, 0, s[34:35]
	v_cndmask_b32_e64 v245, v33, 0, s[34:35]
	v_fmac_f32_dpp v208, v206, v74 row_ror:15 row_mask:0xf bank_mask:0xf
	v_fmac_f32_dpp v209, v207, v75 row_ror:15 row_mask:0xf bank_mask:0xf
	v_fmac_f32_dpp v246, v244, v108 row_ror:15 row_mask:0xf bank_mask:0xf
	v_fmac_f32_dpp v247, v245, v109 row_ror:15 row_mask:0xf bank_mask:0xf
	v_pk_mul_f32 v[214:215], v[254:255], v[208:209]
	v_exp_f32_e32 v214, v214
	v_exp_f32_e32 v215, v215
	s_nop 0
	v_pk_add_f32 v[214:215], v[214:215], v[252:253]
	v_rcp_f32_e32 v214, v214
	v_rcp_f32_e32 v215, v215
	s_nop 0
	v_pk_mul_f32 v[208:209], v[208:209], v[214:215]
	v_pk_mul_f32 v[246:247], v[246:247], v[208:209]
	v_cvt_pk_bf16_f32 v115, v212, v213
	s_nop 0
	v_cndmask_b32_e64 v210, v38, v46, vcc
	v_cndmask_b32_e64 v211, v39, v47, vcc
	v_cndmask_b32_e64 v248, v34, v42, vcc
	v_cndmask_b32_e64 v249, v35, v43, vcc
	v_pk_fma_f32 v[220:221], v[38:39], v[70:71], v[86:87]
	v_pk_fma_f32 v[242:243], v[34:35], v[102:103], v[124:125]
	v_fmac_f32_dpp v220, v210, v66 row_ror:1 row_mask:0xf bank_mask:0xf bound_ctrl:1
	v_fmac_f32_dpp v221, v211, v67 row_ror:1 row_mask:0xf bank_mask:0xf bound_ctrl:1
	v_fmac_f32_dpp v242, v248, v94 row_ror:1 row_mask:0xf bank_mask:0xf bound_ctrl:1
	v_fmac_f32_dpp v243, v249, v95 row_ror:1 row_mask:0xf bank_mask:0xf bound_ctrl:1
	v_cndmask_b32_e64 v210, v38, 0, s[34:35]
	v_cndmask_b32_e64 v211, v39, 0, s[34:35]
	v_cndmask_b32_e64 v248, v34, 0, s[34:35]
	v_cndmask_b32_e64 v249, v35, 0, s[34:35]
	v_fmac_f32_dpp v220, v210, v76 row_ror:15 row_mask:0xf bank_mask:0xf
	v_fmac_f32_dpp v221, v211, v77 row_ror:15 row_mask:0xf bank_mask:0xf
	v_fmac_f32_dpp v242, v248, v110 row_ror:15 row_mask:0xf bank_mask:0xf
	v_fmac_f32_dpp v243, v249, v111 row_ror:15 row_mask:0xf bank_mask:0xf
	v_pk_mul_f32 v[250:251], v[254:255], v[220:221]
	v_exp_f32_e32 v250, v250
	v_exp_f32_e32 v251, v251
	s_nop 0
	v_pk_add_f32 v[250:251], v[250:251], v[252:253]
	v_rcp_f32_e32 v250, v250
	v_rcp_f32_e32 v251, v251
	s_nop 0
	v_pk_mul_f32 v[220:221], v[220:221], v[250:251]
	v_pk_mul_f32 v[242:243], v[242:243], v[220:221]
	s_nop 0
	s_nop 0
	v_lshl_add_u64 v[78:79], s[40:41], 0, v[164:165]
	s_movk_i32 s6, 0x1000
	v_cvt_pk_bf16_f32 v114, v240, v241
	v_add_co_u32_e64 v48, s[40:41], s6, v78
	s_nop 0
	s_nop 0
	v_addc_co_u32_e64 v49, s[40:41], 0, v79, s[40:41]
	global_store_dwordx4 v[78:79], v[116:119], off offset:2048
	global_store_dwordx4 v[48:49], v[112:115], off
	v_cvt_pk_bf16_f32 v106, v246, v247
	v_cvt_pk_bf16_f32 v107, v242, v243
	global_store_dwordx4 v[48:49], v[104:107], off offset:2048
	s_and_saveexec_b64 s[40:41], s[38:39]
	s_cbranch_execz .LBB0_1417
	v_mov_b32_e32 v181, v165
	v_lshl_add_u64 v[40:41], s[52:53], 0, v[180:181]
	v_mov_b64_e32 v[42:43], s[0:1]
	s_movk_i32 s31, 0x2c00
	v_mad_u64_u32 v[42:43], s[6:7], v40, s31, v[42:43]
	v_mad_i32_i24 v43, v41, s31, v43
	v_lshl_add_u64 v[40:41], s[16:17], 1, v[42:43]
	s_lshl_b32 s48, s5, 1
	v_lshl_add_u64 v[40:41], v[40:41], 0, s[48:49]
	v_mov_b32_e32 v179, v165
	s_movk_i32 s66, 0x2c00
	v_lshl_add_u64 v[40:41], v[40:41], 0, v[178:179]
	v_cvt_pk_bf16_f32 v36, v36, v37
	v_cvt_pk_bf16_f32 v37, v38, v39
	global_store_dwordx2 v[40:41], v[36:37], off offset:8
	v_cvt_pk_bf16_f32 v32, v32, v33
	v_cvt_pk_bf16_f32 v33, v34, v35
	global_store_dwordx2 v[40:41], v[32:33], off offset:264
.LBB0_1417:
	s_or_b64 exec, exec, s[40:41]
	v_cndmask_b32_e64 v204, v28, 0, vcc
	v_cndmask_b32_e64 v205, v29, 0, vcc
	v_cndmask_b32_e64 v222, v24, 0, vcc
	v_cndmask_b32_e64 v223, v25, 0, vcc
	v_pk_fma_f32 v[206:207], v[28:29], v[68:69], v[84:85]
	v_pk_fma_f32 v[244:245], v[24:25], v[100:101], v[122:123]
	v_fmac_f32_dpp v206, v204, v64 row_ror:1 row_mask:0xf bank_mask:0xf bound_ctrl:1
	v_fmac_f32_dpp v207, v205, v65 row_ror:1 row_mask:0xf bank_mask:0xf bound_ctrl:1
	v_fmac_f32_dpp v244, v222, v92 row_ror:1 row_mask:0xf bank_mask:0xf bound_ctrl:1
	v_fmac_f32_dpp v245, v223, v93 row_ror:1 row_mask:0xf bank_mask:0xf bound_ctrl:1
	v_cndmask_b32_e64 v204, v28, v20, s[34:35]
	v_cndmask_b32_e64 v205, v29, v21, s[34:35]
	v_cndmask_b32_e64 v222, v24, v16, s[34:35]
	v_cndmask_b32_e64 v223, v25, v17, s[34:35]
	v_fmac_f32_dpp v206, v204, v74 row_ror:15 row_mask:0xf bank_mask:0xf
	v_fmac_f32_dpp v207, v205, v75 row_ror:15 row_mask:0xf bank_mask:0xf
	v_fmac_f32_dpp v244, v222, v108 row_ror:15 row_mask:0xf bank_mask:0xf
	v_fmac_f32_dpp v245, v223, v109 row_ror:15 row_mask:0xf bank_mask:0xf
	v_pk_mul_f32 v[208:209], v[254:255], v[206:207]
	v_exp_f32_e32 v208, v208
	v_exp_f32_e32 v209, v209
	s_nop 0
	v_pk_add_f32 v[208:209], v[208:209], v[252:253]
	v_rcp_f32_e32 v208, v208
	v_rcp_f32_e32 v209, v209
	s_nop 0
	v_pk_mul_f32 v[206:207], v[206:207], v[208:209]
	v_pk_mul_f32 v[244:245], v[244:245], v[206:207]
	s_nop 0
	s_nop 0
	v_cndmask_b32_e64 v214, v30, 0, vcc
	v_cndmask_b32_e64 v215, v31, 0, vcc
	v_cndmask_b32_e64 v212, v26, 0, vcc
	v_cndmask_b32_e64 v213, v27, 0, vcc
	v_pk_fma_f32 v[210:211], v[30:31], v[70:71], v[86:87]
	v_pk_fma_f32 v[248:249], v[26:27], v[102:103], v[124:125]
	v_fmac_f32_dpp v210, v214, v66 row_ror:1 row_mask:0xf bank_mask:0xf bound_ctrl:1
	v_fmac_f32_dpp v211, v215, v67 row_ror:1 row_mask:0xf bank_mask:0xf bound_ctrl:1
	v_fmac_f32_dpp v248, v212, v94 row_ror:1 row_mask:0xf bank_mask:0xf bound_ctrl:1
	v_fmac_f32_dpp v249, v213, v95 row_ror:1 row_mask:0xf bank_mask:0xf bound_ctrl:1
	v_cndmask_b32_e64 v214, v30, v22, s[34:35]
	v_cndmask_b32_e64 v215, v31, v23, s[34:35]
	v_cndmask_b32_e64 v212, v26, v18, s[34:35]
	v_cndmask_b32_e64 v213, v27, v19, s[34:35]
	v_fmac_f32_dpp v210, v214, v76 row_ror:15 row_mask:0xf bank_mask:0xf
	v_fmac_f32_dpp v211, v215, v77 row_ror:15 row_mask:0xf bank_mask:0xf
	v_fmac_f32_dpp v248, v212, v110 row_ror:15 row_mask:0xf bank_mask:0xf
	v_fmac_f32_dpp v249, v213, v111 row_ror:15 row_mask:0xf bank_mask:0xf
	v_pk_mul_f32 v[220:221], v[254:255], v[210:211]
	v_exp_f32_e32 v220, v220
	v_exp_f32_e32 v221, v221
	s_nop 0
	v_pk_add_f32 v[220:221], v[220:221], v[252:253]
	v_rcp_f32_e32 v220, v220
	v_rcp_f32_e32 v221, v221
	s_nop 0
	v_pk_mul_f32 v[210:211], v[210:211], v[220:221]
	v_pk_mul_f32 v[248:249], v[248:249], v[210:211]
	s_nop 0
	s_nop 0
	v_or_b32_e32 v32, s85, v200
	s_ashr_i32 s6, s85, 8
	s_mul_hi_i32 s7, s6, 0x160000
	s_mul_i32 s6, s6, 0x160000
	v_lshlrev_b32_e32 v32, 6, v32
	s_movk_i32 s31, 0x33c0
	v_and_or_b32 v32, v32, s31, v82
	s_add_u32 s40, s86, s6
	s_addc_u32 s41, s87, s7
	v_lshlrev_b32_e32 v164, 1, v32
	v_cvt_pk_bf16_f32 v98, v244, v245
	v_cvt_pk_bf16_f32 v99, v248, v249
	global_store_dwordx4 v164, v[96:99], s[40:41]
	s_and_saveexec_b64 s[6:7], s[36:37]
	s_cbranch_execz .LBB0_1419
	v_mov_b64_e32 v[32:33], s[0:1]
	v_mad_i64_i32 v[32:33], s[36:37], v156, s66, v[32:33]
	v_lshl_add_u64 v[32:33], s[16:17], 1, v[32:33]
	s_lshl_b32 s48, s5, 1
	v_lshl_add_u64 v[32:33], v[32:33], 0, s[48:49]
	v_mov_b32_e32 v179, v165
	v_lshl_add_u64 v[32:33], v[32:33], 0, v[178:179]
	v_cvt_pk_bf16_f32 v34, v28, v29
	v_cvt_pk_bf16_f32 v35, v30, v31
	global_store_dwordx2 v[32:33], v[34:35], off offset:8
	v_cvt_pk_bf16_f32 v34, v24, v25
	v_cvt_pk_bf16_f32 v35, v26, v27
	global_store_dwordx2 v[32:33], v[34:35], off offset:264
.LBB0_1419:
	s_or_b64 exec, exec, s[6:7]
	v_cndmask_b32_e64 v250, v20, v28, vcc
	v_cndmask_b32_e64 v251, v21, v29, vcc
	v_cndmask_b32_e64 v240, v16, v24, vcc
	v_cndmask_b32_e64 v241, v17, v25, vcc
	v_pk_fma_f32 v[246:247], v[20:21], v[68:69], v[84:85]
	v_pk_fma_f32 v[242:243], v[16:17], v[100:101], v[122:123]
	v_fmac_f32_dpp v246, v250, v64 row_ror:1 row_mask:0xf bank_mask:0xf bound_ctrl:1
	v_fmac_f32_dpp v247, v251, v65 row_ror:1 row_mask:0xf bank_mask:0xf bound_ctrl:1
	v_fmac_f32_dpp v242, v240, v92 row_ror:1 row_mask:0xf bank_mask:0xf bound_ctrl:1
	v_fmac_f32_dpp v243, v241, v93 row_ror:1 row_mask:0xf bank_mask:0xf bound_ctrl:1
	v_cndmask_b32_e64 v250, v20, v12, s[34:35]
	v_cndmask_b32_e64 v251, v21, v13, s[34:35]
	v_cndmask_b32_e64 v240, v16, v8, s[34:35]
	v_cndmask_b32_e64 v241, v17, v9, s[34:35]
	v_fmac_f32_dpp v246, v250, v74 row_ror:15 row_mask:0xf bank_mask:0xf
	v_fmac_f32_dpp v247, v251, v75 row_ror:15 row_mask:0xf bank_mask:0xf
	v_fmac_f32_dpp v242, v240, v108 row_ror:15 row_mask:0xf bank_mask:0xf
	v_fmac_f32_dpp v243, v241, v109 row_ror:15 row_mask:0xf bank_mask:0xf
	v_pk_mul_f32 v[204:205], v[254:255], v[246:247]
	v_exp_f32_e32 v204, v204
	v_exp_f32_e32 v205, v205
	s_nop 0
	v_pk_add_f32 v[204:205], v[204:205], v[252:253]
	v_rcp_f32_e32 v204, v204
	v_rcp_f32_e32 v205, v205
	s_nop 0
	v_pk_mul_f32 v[246:247], v[246:247], v[204:205]
	v_pk_mul_f32 v[242:243], v[242:243], v[246:247]
	s_nop 0
	s_nop 0
	v_cndmask_b32_e64 v222, v22, v30, vcc
	v_cndmask_b32_e64 v223, v23, v31, vcc
	v_cndmask_b32_e64 v206, v18, v26, vcc
	v_cndmask_b32_e64 v207, v19, v27, vcc
	v_pk_fma_f32 v[208:209], v[22:23], v[70:71], v[86:87]
	v_pk_fma_f32 v[214:215], v[18:19], v[102:103], v[124:125]
	v_fmac_f32_dpp v208, v222, v66 row_ror:1 row_mask:0xf bank_mask:0xf bound_ctrl:1
	v_fmac_f32_dpp v209, v223, v67 row_ror:1 row_mask:0xf bank_mask:0xf bound_ctrl:1
	v_fmac_f32_dpp v214, v206, v94 row_ror:1 row_mask:0xf bank_mask:0xf bound_ctrl:1
	v_fmac_f32_dpp v215, v207, v95 row_ror:1 row_mask:0xf bank_mask:0xf bound_ctrl:1
	v_cndmask_b32_e64 v222, v22, v14, s[34:35]
	v_cndmask_b32_e64 v223, v23, v15, s[34:35]
	v_cndmask_b32_e64 v206, v18, v10, s[34:35]
	v_cndmask_b32_e64 v207, v19, v11, s[34:35]
	v_fmac_f32_dpp v208, v222, v76 row_ror:15 row_mask:0xf bank_mask:0xf
	v_fmac_f32_dpp v209, v223, v77 row_ror:15 row_mask:0xf bank_mask:0xf
	v_fmac_f32_dpp v214, v206, v110 row_ror:15 row_mask:0xf bank_mask:0xf
	v_fmac_f32_dpp v215, v207, v111 row_ror:15 row_mask:0xf bank_mask:0xf
	v_pk_mul_f32 v[212:213], v[254:255], v[208:209]
	v_exp_f32_e32 v212, v212
	v_exp_f32_e32 v213, v213
	s_nop 0
	v_pk_add_f32 v[212:213], v[212:213], v[252:253]
	v_rcp_f32_e32 v212, v212
	v_rcp_f32_e32 v213, v213
	s_nop 0
	v_pk_mul_f32 v[208:209], v[208:209], v[212:213]
	v_pk_mul_f32 v[214:215], v[214:215], v[208:209]
	s_nop 0
	v_cndmask_b32_e64 v210, v12, v20, vcc
	v_cndmask_b32_e64 v211, v13, v21, vcc
	v_cndmask_b32_e64 v220, v8, v16, vcc
	v_cndmask_b32_e64 v221, v9, v17, vcc
	v_pk_fma_f32 v[244:245], v[12:13], v[68:69], v[84:85]
	v_pk_fma_f32 v[248:249], v[8:9], v[100:101], v[122:123]
	v_fmac_f32_dpp v244, v210, v64 row_ror:1 row_mask:0xf bank_mask:0xf bound_ctrl:1
	v_fmac_f32_dpp v245, v211, v65 row_ror:1 row_mask:0xf bank_mask:0xf bound_ctrl:1
	v_fmac_f32_dpp v248, v220, v92 row_ror:1 row_mask:0xf bank_mask:0xf bound_ctrl:1
	v_fmac_f32_dpp v249, v221, v93 row_ror:1 row_mask:0xf bank_mask:0xf bound_ctrl:1
	v_cndmask_b32_e64 v210, v12, v4, s[34:35]
	v_cndmask_b32_e64 v211, v13, v5, s[34:35]
	v_cndmask_b32_e64 v220, v8, v0, s[34:35]
	v_cndmask_b32_e64 v221, v9, v1, s[34:35]
	v_fmac_f32_dpp v244, v210, v74 row_ror:15 row_mask:0xf bank_mask:0xf
	v_fmac_f32_dpp v245, v211, v75 row_ror:15 row_mask:0xf bank_mask:0xf
	v_fmac_f32_dpp v248, v220, v108 row_ror:15 row_mask:0xf bank_mask:0xf
	v_fmac_f32_dpp v249, v221, v109 row_ror:15 row_mask:0xf bank_mask:0xf
	v_pk_mul_f32 v[250:251], v[254:255], v[244:245]
	v_exp_f32_e32 v250, v250
	v_exp_f32_e32 v251, v251
	s_nop 0
	v_pk_add_f32 v[250:251], v[250:251], v[252:253]
	v_rcp_f32_e32 v250, v250
	v_rcp_f32_e32 v251, v251
	s_nop 0
	v_pk_mul_f32 v[244:245], v[244:245], v[250:251]
	v_pk_mul_f32 v[248:249], v[248:249], v[244:245]
	s_nop 0
	v_cvt_pk_bf16_f32 v90, v242, v243
	s_nop 0
	s_nop 0
	v_cvt_pk_bf16_f32 v91, v214, v215
	s_nop 0
	v_cndmask_b32_e64 v240, v14, v22, vcc
	v_cndmask_b32_e64 v241, v15, v23, vcc
	v_cndmask_b32_e64 v246, v10, v18, vcc
	v_cndmask_b32_e64 v247, v11, v19, vcc
	v_pk_fma_f32 v[204:205], v[14:15], v[70:71], v[86:87]
	v_pk_fma_f32 v[222:223], v[10:11], v[102:103], v[124:125]
	v_fmac_f32_dpp v204, v240, v66 row_ror:1 row_mask:0xf bank_mask:0xf bound_ctrl:1
	v_fmac_f32_dpp v205, v241, v67 row_ror:1 row_mask:0xf bank_mask:0xf bound_ctrl:1
	v_fmac_f32_dpp v222, v246, v94 row_ror:1 row_mask:0xf bank_mask:0xf bound_ctrl:1
	v_fmac_f32_dpp v223, v247, v95 row_ror:1 row_mask:0xf bank_mask:0xf bound_ctrl:1
	v_cndmask_b32_e64 v240, v14, v6, s[34:35]
	v_cndmask_b32_e64 v241, v15, v7, s[34:35]
	v_cndmask_b32_e64 v246, v10, v2, s[34:35]
	v_cndmask_b32_e64 v247, v11, v3, s[34:35]
	v_fmac_f32_dpp v204, v240, v76 row_ror:15 row_mask:0xf bank_mask:0xf
	v_fmac_f32_dpp v205, v241, v77 row_ror:15 row_mask:0xf bank_mask:0xf
	v_fmac_f32_dpp v222, v246, v110 row_ror:15 row_mask:0xf bank_mask:0xf
	v_fmac_f32_dpp v223, v247, v111 row_ror:15 row_mask:0xf bank_mask:0xf
	v_pk_mul_f32 v[206:207], v[254:255], v[204:205]
	v_exp_f32_e32 v206, v206
	v_exp_f32_e32 v207, v207
	s_nop 0
	v_pk_add_f32 v[206:207], v[206:207], v[252:253]
	v_rcp_f32_e32 v206, v206
	v_rcp_f32_e32 v207, v207
	s_nop 0
	v_pk_mul_f32 v[204:205], v[204:205], v[206:207]
	v_pk_mul_f32 v[222:223], v[222:223], v[204:205]
	s_nop 0
	s_nop 0
	v_cndmask_b32_e64 v208, v4, v12, vcc
	v_cndmask_b32_e64 v209, v5, v13, vcc
	v_cndmask_b32_e64 v212, v0, v8, vcc
	v_cndmask_b32_e64 v213, v1, v9, vcc
	v_pk_fma_f32 v[210:211], v[4:5], v[68:69], v[84:85]
	v_pk_fma_f32 v[220:221], v[0:1], v[100:101], v[122:123]
	v_fmac_f32_dpp v210, v208, v64 row_ror:1 row_mask:0xf bank_mask:0xf bound_ctrl:1
	v_fmac_f32_dpp v211, v209, v65 row_ror:1 row_mask:0xf bank_mask:0xf bound_ctrl:1
	v_fmac_f32_dpp v220, v212, v92 row_ror:1 row_mask:0xf bank_mask:0xf bound_ctrl:1
	v_fmac_f32_dpp v221, v213, v93 row_ror:1 row_mask:0xf bank_mask:0xf bound_ctrl:1
	v_cndmask_b32_e64 v208, v4, 0, s[34:35]
	v_cndmask_b32_e64 v209, v5, 0, s[34:35]
	v_cndmask_b32_e64 v212, v0, 0, s[34:35]
	v_cndmask_b32_e64 v213, v1, 0, s[34:35]
	v_fmac_f32_dpp v210, v208, v74 row_ror:15 row_mask:0xf bank_mask:0xf
	v_fmac_f32_dpp v211, v209, v75 row_ror:15 row_mask:0xf bank_mask:0xf
	v_fmac_f32_dpp v220, v212, v108 row_ror:15 row_mask:0xf bank_mask:0xf
	v_fmac_f32_dpp v221, v213, v109 row_ror:15 row_mask:0xf bank_mask:0xf
	v_pk_mul_f32 v[244:245], v[254:255], v[210:211]
	v_exp_f32_e32 v244, v244
	v_exp_f32_e32 v245, v245
	s_nop 0
	v_pk_add_f32 v[244:245], v[244:245], v[252:253]
	v_rcp_f32_e32 v244, v244
	v_rcp_f32_e32 v245, v245
	s_nop 0
	v_pk_mul_f32 v[210:211], v[210:211], v[244:245]
	v_pk_mul_f32 v[220:221], v[220:221], v[210:211]
	v_cvt_pk_bf16_f32 v83, v222, v223
	s_nop 0
	v_cndmask_b32_e64 v250, v6, v14, vcc
	v_cndmask_b32_e64 v251, v7, v15, vcc
	v_cndmask_b32_e64 v242, v2, v10, vcc
	v_cndmask_b32_e64 v243, v3, v11, vcc
	v_pk_fma_f32 v[214:215], v[6:7], v[70:71], v[86:87]
	v_pk_fma_f32 v[240:241], v[2:3], v[102:103], v[124:125]
	v_fmac_f32_dpp v214, v250, v66 row_ror:1 row_mask:0xf bank_mask:0xf bound_ctrl:1
	v_fmac_f32_dpp v215, v251, v67 row_ror:1 row_mask:0xf bank_mask:0xf bound_ctrl:1
	v_fmac_f32_dpp v240, v242, v94 row_ror:1 row_mask:0xf bank_mask:0xf bound_ctrl:1
	v_fmac_f32_dpp v241, v243, v95 row_ror:1 row_mask:0xf bank_mask:0xf bound_ctrl:1
	v_cndmask_b32_e64 v250, v6, 0, s[34:35]
	v_cndmask_b32_e64 v251, v7, 0, s[34:35]
	v_cndmask_b32_e64 v242, v2, 0, s[34:35]
	v_cndmask_b32_e64 v243, v3, 0, s[34:35]
	v_fmac_f32_dpp v214, v250, v76 row_ror:15 row_mask:0xf bank_mask:0xf
	v_fmac_f32_dpp v215, v251, v77 row_ror:15 row_mask:0xf bank_mask:0xf
	v_fmac_f32_dpp v240, v242, v110 row_ror:15 row_mask:0xf bank_mask:0xf
	v_fmac_f32_dpp v241, v243, v111 row_ror:15 row_mask:0xf bank_mask:0xf
	v_pk_mul_f32 v[246:247], v[254:255], v[214:215]
	v_exp_f32_e32 v246, v246
	v_exp_f32_e32 v247, v247
	s_nop 0
	v_pk_add_f32 v[246:247], v[246:247], v[252:253]
	v_rcp_f32_e32 v246, v246
	v_rcp_f32_e32 v247, v247
	s_nop 0
	v_pk_mul_f32 v[214:215], v[214:215], v[246:247]
	v_pk_mul_f32 v[240:241], v[240:241], v[214:215]
	s_nop 0
	s_nop 0
	v_lshl_add_u64 v[32:33], s[40:41], 0, v[164:165]
	s_movk_i32 s6, 0x1000
	v_cvt_pk_bf16_f32 v82, v248, v249
	v_add_co_u32_e64 v16, s[36:37], s6, v32
	s_nop 0
	s_nop 0
	v_addc_co_u32_e64 v17, s[36:37], 0, v33, s[36:37]
	global_store_dwordx4 v[32:33], v[88:91], off offset:2048
	global_store_dwordx4 v[16:17], v[80:83], off
	v_cvt_pk_bf16_f32 v74, v220, v221
	v_cvt_pk_bf16_f32 v75, v240, v241
	global_store_dwordx4 v[16:17], v[72:75], off offset:2048
	s_and_saveexec_b64 s[34:35], s[38:39]
	s_cbranch_execz .LBB0_1392
	v_mov_b32_e32 v181, v165
	v_lshl_add_u64 v[8:9], s[10:11], 0, v[180:181]
	v_mov_b64_e32 v[10:11], s[0:1]
	s_movk_i32 s10, 0x2c00
	v_mad_u64_u32 v[10:11], s[6:7], v8, s10, v[10:11]
	v_mad_i32_i24 v11, v9, s10, v11
	v_lshl_add_u64 v[8:9], s[16:17], 1, v[10:11]
	s_lshl_b32 s48, s5, 1
	v_lshl_add_u64 v[8:9], v[8:9], 0, s[48:49]
	v_mov_b32_e32 v179, v165
	s_movk_i32 s66, 0x2c00
	v_lshl_add_u64 v[8:9], v[8:9], 0, v[178:179]
	v_cvt_pk_bf16_f32 v4, v4, v5
	v_cvt_pk_bf16_f32 v5, v6, v7
	global_store_dwordx2 v[8:9], v[4:5], off offset:8
	v_cvt_pk_bf16_f32 v0, v0, v1
	v_cvt_pk_bf16_f32 v1, v2, v3
	global_store_dwordx2 v[8:9], v[0:1], off offset:264
	s_branch .LBB0_1392
